# kfix: gains loaded once + 4 row pieces prefetched; attention unit prologue: 32 serialized gain loads hoisted in two batches; ret_out step A: 32 K fragment loads hoisted (was load-wait per fragment)
# speedup vs baseline: 1.0236x; 1.0102x over previous
.LBB0_319:
	s_or_b64 exec, exec, s[0:1]
	s_and_b64 vcc, exec, s[78:79]
	s_waitcnt lgkmcnt(0)
	s_barrier
	s_cbranch_vccnz .LBB0_376
	v_mov_b32_e32 v3, v206
	v_readlane_b32 s0, v254, 19
	v_ashrrev_i32_e32 v0, 6, v3
	s_nop 0
	v_add_u32_e32 v2, s0, v0
	v_mov_b32_e32 v0, s8
	v_add_co_u32_e32 v4, vcc, 0xd0000, v0
	v_mov_b32_e32 v0, s9
	s_nop 0
	v_addc_co_u32_e32 v5, vcc, 0, v0, vcc
	flat_load_dwordx2 v[6:7], v[4:5] offset:80 sc1
	s_movk_i32 s0, 0x4000
	flat_load_dwordx2 v[4:5], v[4:5] offset:88 sc1
	v_cmp_gt_i32_e32 vcc, s0, v2
	s_waitcnt vmcnt(0) lgkmcnt(0)
	v_readfirstlane_b32 s5, v7
	v_readfirstlane_b32 s4, v6
	v_readfirstlane_b32 s13, v5
	v_readfirstlane_b32 s12, v4
	s_and_saveexec_b64 s[0:1], vcc
	v_readlane_b32 s14, v255, 60
	v_readlane_b32 s18, v255, 62
	v_readlane_b32 s30, v254, 0
	s_movk_i32 s10, 0x7fff
	v_readlane_b32 s15, v255, 61
	v_readlane_b32 s19, v255, 63
	v_readlane_b32 s31, v254, 1
	s_cbranch_execz .LBB0_323
	v_and_b32_e32 v4, 64, v228
	v_xor_b32_e32 v0, 1, v228
	v_add_u32_e32 v8, 64, v4
	v_cmp_lt_i32_e32 vcc, v0, v8
	v_and_b32_e32 v16, 63, v3
	v_and_b32_e32 v9, 31, v3
	v_cndmask_b32_e32 v0, v228, v0, vcc
	v_lshlrev_b32_e32 v26, 2, v0
	v_xor_b32_e32 v0, 2, v228
	v_cmp_lt_i32_e32 vcc, v0, v8
	v_cmp_gt_u32_e64 s[36:37], 32, v16
	s_nop 0
	v_cndmask_b32_e32 v0, v228, v0, vcc
	v_lshlrev_b32_e32 v27, 2, v0
	v_xor_b32_e32 v0, 4, v228
	v_cmp_lt_i32_e32 vcc, v0, v8
	s_nop 1
	v_cndmask_b32_e32 v0, v228, v0, vcc
	v_lshlrev_b32_e32 v28, 2, v0
	v_xor_b32_e32 v0, 8, v228
	v_cmp_lt_i32_e32 vcc, v0, v8
	s_nop 1
	v_cndmask_b32_e32 v0, v228, v0, vcc
	v_lshlrev_b32_e32 v29, 2, v0
	v_lshlrev_b32_e32 v0, 5, v3
	v_xor_b32_e32 v3, 16, v228
	v_cmp_lt_i32_e32 vcc, v3, v8
	v_and_b32_e32 v0, 0x1e0, v0
	v_lshl_add_u64 v[4:5], s[4:5], 0, v[0:1]
	v_cndmask_b32_e32 v3, v228, v3, vcc
	v_lshlrev_b32_e32 v30, 2, v3
	v_xor_b32_e32 v3, 32, v228
	v_cmp_lt_i32_e32 vcc, v3, v8
	v_lshlrev_b32_e32 v0, 2, v16
	s_mov_b64 s[4:5], 0x30f00000
	v_cndmask_b32_e32 v3, v228, v3, vcc
	v_lshlrev_b32_e32 v31, 2, v3
	v_ashrrev_i32_e32 v3, 31, v2
	v_lshlrev_b64 v[10:11], 7, v[2:3]
	v_lshl_or_b32 v8, v9, 2, v10
	v_lshl_or_b32 v10, v16, 1, v10
	v_lshlrev_b64 v[12:13], 8, v[2:3]
	v_mov_b32_e32 v9, v11
	v_lshl_add_u64 v[10:11], v[10:11], 0, s[4:5]
	v_or_b32_e32 v12, v12, v0
	s_mov_b64 s[4:5], 0x25b00000
	v_lshlrev_b64 v[14:15], 12, v[2:3]
	v_lshl_add_u64 v[6:7], s[12:13], 0, v[0:1]
	v_lshl_add_u64 v[12:13], v[12:13], 0, s[4:5]
	v_lshl_or_b32 v14, v16, 4, v14
	s_mov_b64 s[4:5], 0
	flat_load_dwordx2 v[176:177], v[4:5]
	flat_load_dwordx2 v[178:179], v[4:5] offset:8
	flat_load_dwordx2 v[180:181], v[4:5] offset:16
	flat_load_dwordx2 v[182:183], v[4:5] offset:24
	s_waitcnt vmcnt(0) lgkmcnt(0)
.LBB0_322:
	v_lshl_add_u64 v[16:17], s[8:9], 0, v[14:15]
	v_add_co_u32_e32 v16, vcc, 0x28f00000, v16
	s_mov_b32 s2, 0x1100000
	s_nop 0
	v_addc_co_u32_e32 v17, vcc, 0, v17, vcc
	flat_load_dwordx4 v[32:35], v[16:17]
	flat_load_dwordx4 v[184:187], v[16:17] offset:1024
	flat_load_dwordx4 v[188:191], v[16:17] offset:2048
	flat_load_dwordx4 v[192:195], v[16:17] offset:3072
	v_add_u32_e32 v2, s52, v2
	v_lshl_add_u64 v[14:15], v[14:15], 0, s[30:31]
	s_waitcnt vmcnt(0) lgkmcnt(0)
	v_and_b32_e32 v23, 0xffff0000, v33
	v_and_b32_e32 v22, 0xffff0000, v32
	v_lshlrev_b32_e32 v25, 16, v33
	v_lshlrev_b32_e32 v24, 16, v32
	v_pk_mul_f32 v[18:19], v[22:23], v[22:23]
	v_lshlrev_b32_e32 v21, 16, v35
	v_pk_fma_f32 v[32:33], v[24:25], v[24:25], v[18:19]
	v_and_b32_e32 v19, 0xffff0000, v35
	v_add_f32_e32 v0, v32, v33
	v_mov_b32_e32 v32, v176
	v_mov_b32_e32 v33, v177
	v_and_b32_e32 v18, 0xffff0000, v34
	v_lshlrev_b32_e32 v20, 16, v34
	v_pk_mul_f32 v[34:35], v[18:19], v[18:19]
	s_nop 0
	v_pk_fma_f32 v[34:35], v[20:21], v[20:21], v[34:35]
	s_nop 0
	v_add_f32_e32 v0, v34, v0
	v_add_f32_e32 v0, v35, v0
	ds_bpermute_b32 v3, v26, v0
	s_waitcnt lgkmcnt(0)
	v_add_f32_e32 v0, v0, v3
	ds_bpermute_b32 v3, v27, v0
	s_waitcnt lgkmcnt(0)
	v_add_f32_e32 v0, v0, v3
	ds_bpermute_b32 v3, v28, v0
	s_waitcnt lgkmcnt(0)
	v_add_f32_e32 v0, v0, v3
	ds_bpermute_b32 v3, v29, v0
	s_waitcnt lgkmcnt(0)
	v_add_f32_e32 v0, v0, v3
	v_fmamk_f32 v0, v0, 0x3c000000, v207
	v_cmp_gt_f32_e32 vcc, s87, v0
	v_mul_f32_e32 v3, 0x4b800000, v0
	s_nop 0
	v_cndmask_b32_e32 v0, v0, v3, vcc
	v_rsq_f32_e32 v0, v0
	s_nop 0
	v_mul_f32_e32 v3, 0x45800000, v0
	v_cndmask_b32_e32 v0, v0, v3, vcc
	v_mul_f32_e32 v3, v0, v24
	v_mul_f32_e32 v22, v0, v22
	v_mul_f32_e32 v23, v0, v23
	v_mul_f32_e32 v18, v0, v18

	v_mul_f32_e32 v3, v32, v3
	v_mul_f32_e32 v22, v33, v22
	v_cvt_pk_bf16_f32 v22, v3, v22
	v_mul_f32_e32 v3, v0, v25
	v_mov_b32_e32 v24, v178
	v_mov_b32_e32 v25, v179
	v_mul_f32_e32 v23, v25, v23
	v_mul_f32_e32 v3, v24, v3
	v_cvt_pk_bf16_f32 v23, v3, v23
	v_mov_b32_e32 v24, v180
	v_mov_b32_e32 v25, v181
	v_mul_f32_e32 v3, v0, v20
	v_mul_f32_e32 v3, v24, v3
	v_mul_f32_e32 v18, v25, v18
	v_cvt_pk_bf16_f32 v24, v3, v18
	v_mul_f32_e32 v3, v0, v21
	v_mov_b32_e32 v20, v182
	v_mov_b32_e32 v21, v183
	v_mul_f32_e32 v0, v0, v19
	v_mul_f32_e32 v3, v20, v3
	v_mul_f32_e32 v0, v21, v0
	v_cvt_pk_bf16_f32 v25, v3, v0
	v_mov_b32_e32 v32, v184
	v_mov_b32_e32 v33, v185
	v_mov_b32_e32 v34, v186
	v_mov_b32_e32 v35, v187
	v_lshlrev_b32_e32 v21, 16, v35
	flat_store_dwordx4 v[16:17], v[22:25]
	v_lshlrev_b32_e32 v20, 16, v34
	s_nop 0
	v_and_b32_e32 v23, 0xffff0000, v33
	v_and_b32_e32 v22, 0xffff0000, v32
	v_lshlrev_b32_e32 v25, 16, v33
	v_lshlrev_b32_e32 v24, 16, v32
	v_pk_mul_f32 v[18:19], v[22:23], v[22:23]
	s_nop 0
	v_pk_fma_f32 v[32:33], v[24:25], v[24:25], v[18:19]
	v_and_b32_e32 v19, 0xffff0000, v35
	v_add_f32_e32 v0, v32, v33
	v_mov_b32_e32 v32, v176
	v_mov_b32_e32 v33, v177
	v_and_b32_e32 v18, 0xffff0000, v34
	v_pk_mul_f32 v[34:35], v[18:19], v[18:19]
	s_nop 0
	v_pk_fma_f32 v[34:35], v[20:21], v[20:21], v[34:35]
	s_nop 0
	v_add_f32_e32 v0, v34, v0
	v_add_f32_e32 v0, v35, v0
	ds_bpermute_b32 v3, v26, v0
	s_waitcnt lgkmcnt(0)
	v_add_f32_e32 v0, v0, v3
	ds_bpermute_b32 v3, v27, v0
	s_waitcnt lgkmcnt(0)
	v_add_f32_e32 v0, v0, v3
	ds_bpermute_b32 v3, v28, v0
	s_waitcnt lgkmcnt(0)
	v_add_f32_e32 v0, v0, v3
	ds_bpermute_b32 v3, v29, v0
	s_waitcnt lgkmcnt(0)
	v_add_f32_e32 v0, v0, v3
	v_fmamk_f32 v0, v0, 0x3c000000, v207
	v_cmp_gt_f32_e32 vcc, s87, v0
	v_mul_f32_e32 v3, 0x4b800000, v0
	s_nop 0
	v_cndmask_b32_e32 v0, v0, v3, vcc
	v_rsq_f32_e32 v0, v0
	s_nop 0
	v_mul_f32_e32 v3, 0x45800000, v0
	v_cndmask_b32_e32 v0, v0, v3, vcc
	v_mul_f32_e32 v3, v0, v24
	v_mul_f32_e32 v22, v0, v22
	v_mul_f32_e32 v23, v0, v23
	v_mul_f32_e32 v18, v0, v18

	v_mul_f32_e32 v3, v32, v3
	v_mul_f32_e32 v22, v33, v22
	v_cvt_pk_bf16_f32 v22, v3, v22
	v_mul_f32_e32 v3, v0, v25
	v_mov_b32_e32 v24, v178
	v_mov_b32_e32 v25, v179
	v_mul_f32_e32 v23, v25, v23
	v_mul_f32_e32 v3, v24, v3
	v_cvt_pk_bf16_f32 v23, v3, v23
	v_mov_b32_e32 v24, v180
	v_mov_b32_e32 v25, v181
	v_mul_f32_e32 v3, v0, v20
	v_mul_f32_e32 v3, v24, v3
	v_mul_f32_e32 v18, v25, v18
	v_cvt_pk_bf16_f32 v24, v3, v18
	v_mul_f32_e32 v3, v0, v21
	v_mov_b32_e32 v20, v182
	v_mov_b32_e32 v21, v183
	v_mul_f32_e32 v0, v0, v19
	v_mul_f32_e32 v3, v20, v3
	v_mul_f32_e32 v0, v21, v0
	v_cvt_pk_bf16_f32 v25, v3, v0
	v_mov_b32_e32 v32, v188
	v_mov_b32_e32 v33, v189
	v_mov_b32_e32 v34, v190
	v_mov_b32_e32 v35, v191
	v_lshlrev_b32_e32 v21, 16, v35
	flat_store_dwordx4 v[16:17], v[22:25] offset:1024
	v_lshlrev_b32_e32 v20, 16, v34
	s_nop 0
	v_and_b32_e32 v23, 0xffff0000, v33
	v_and_b32_e32 v22, 0xffff0000, v32
	v_lshlrev_b32_e32 v25, 16, v33
	v_lshlrev_b32_e32 v24, 16, v32
	v_pk_mul_f32 v[18:19], v[22:23], v[22:23]
	s_nop 0
	v_pk_fma_f32 v[32:33], v[24:25], v[24:25], v[18:19]
	v_and_b32_e32 v19, 0xffff0000, v35
	v_add_f32_e32 v0, v32, v33
	v_mov_b32_e32 v32, v176
	v_mov_b32_e32 v33, v177
	v_and_b32_e32 v18, 0xffff0000, v34
	v_pk_mul_f32 v[34:35], v[18:19], v[18:19]
	s_nop 0
	v_pk_fma_f32 v[34:35], v[20:21], v[20:21], v[34:35]
	s_nop 0
	v_add_f32_e32 v0, v34, v0
	v_add_f32_e32 v0, v35, v0
	ds_bpermute_b32 v3, v26, v0
	s_waitcnt lgkmcnt(0)
	v_add_f32_e32 v0, v0, v3
	ds_bpermute_b32 v3, v27, v0
	s_waitcnt lgkmcnt(0)
	v_add_f32_e32 v0, v0, v3
	ds_bpermute_b32 v3, v28, v0
	s_waitcnt lgkmcnt(0)
	v_add_f32_e32 v0, v0, v3
	ds_bpermute_b32 v3, v29, v0
	s_waitcnt lgkmcnt(0)
	v_add_f32_e32 v0, v0, v3
	v_fmamk_f32 v0, v0, 0x3c000000, v207
	v_cmp_gt_f32_e32 vcc, s87, v0
	v_mul_f32_e32 v3, 0x4b800000, v0
	s_nop 0
	v_cndmask_b32_e32 v0, v0, v3, vcc
	v_rsq_f32_e32 v0, v0
	s_nop 0
	v_mul_f32_e32 v3, 0x45800000, v0
	v_cndmask_b32_e32 v0, v0, v3, vcc
	v_mul_f32_e32 v3, v0, v24
	v_mul_f32_e32 v22, v0, v22
	v_mul_f32_e32 v23, v0, v23
	v_mul_f32_e32 v18, v0, v18

	v_mul_f32_e32 v3, v32, v3
	v_mul_f32_e32 v22, v33, v22
	v_cvt_pk_bf16_f32 v22, v3, v22
	v_mul_f32_e32 v3, v0, v25
	v_mov_b32_e32 v24, v178
	v_mov_b32_e32 v25, v179
	v_mul_f32_e32 v23, v25, v23
	v_mul_f32_e32 v3, v24, v3
	v_cvt_pk_bf16_f32 v23, v3, v23
	v_mov_b32_e32 v24, v180
	v_mov_b32_e32 v25, v181
	v_mul_f32_e32 v3, v0, v20
	v_mul_f32_e32 v3, v24, v3
	v_mul_f32_e32 v18, v25, v18
	v_cvt_pk_bf16_f32 v24, v3, v18
	v_mul_f32_e32 v3, v0, v21
	v_mov_b32_e32 v20, v182
	v_mov_b32_e32 v21, v183
	v_mul_f32_e32 v0, v0, v19
	v_mul_f32_e32 v3, v20, v3
	v_mul_f32_e32 v0, v21, v0
	v_cvt_pk_bf16_f32 v25, v3, v0
	v_mov_b32_e32 v32, v192
	v_mov_b32_e32 v33, v193
	v_mov_b32_e32 v34, v194
	v_mov_b32_e32 v35, v195
	v_lshlrev_b32_e32 v21, 16, v35
	flat_store_dwordx4 v[16:17], v[22:25] offset:2048
	v_lshlrev_b32_e32 v20, 16, v34
	s_nop 0
	v_and_b32_e32 v23, 0xffff0000, v33
	v_and_b32_e32 v22, 0xffff0000, v32
	v_lshlrev_b32_e32 v25, 16, v33
	v_lshlrev_b32_e32 v24, 16, v32
	v_pk_mul_f32 v[18:19], v[22:23], v[22:23]
	s_nop 0
	v_pk_fma_f32 v[32:33], v[24:25], v[24:25], v[18:19]
	v_and_b32_e32 v19, 0xffff0000, v35
	v_add_f32_e32 v0, v32, v33
	v_mov_b32_e32 v32, v176
	v_mov_b32_e32 v33, v177
	v_and_b32_e32 v18, 0xffff0000, v34
	v_pk_mul_f32 v[34:35], v[18:19], v[18:19]
	s_nop 0
	v_pk_fma_f32 v[34:35], v[20:21], v[20:21], v[34:35]
	s_nop 0
	v_add_f32_e32 v0, v34, v0
	v_add_f32_e32 v0, v35, v0
	ds_bpermute_b32 v3, v26, v0
	s_waitcnt lgkmcnt(0)
	v_add_f32_e32 v0, v0, v3
	ds_bpermute_b32 v3, v27, v0
	s_waitcnt lgkmcnt(0)
	v_add_f32_e32 v0, v0, v3
	ds_bpermute_b32 v3, v28, v0
	s_waitcnt lgkmcnt(0)
	v_add_f32_e32 v0, v0, v3
	ds_bpermute_b32 v3, v29, v0
	s_waitcnt lgkmcnt(0)
	v_add_f32_e32 v0, v0, v3
	v_fmamk_f32 v0, v0, 0x3c000000, v207
	v_cmp_gt_f32_e32 vcc, s87, v0
	v_mul_f32_e32 v3, 0x4b800000, v0
	s_nop 0
	v_cndmask_b32_e32 v0, v0, v3, vcc
	v_rsq_f32_e32 v0, v0
	s_nop 0
	v_mul_f32_e32 v3, 0x45800000, v0
	v_cndmask_b32_e32 v0, v0, v3, vcc
	v_mul_f32_e32 v3, v0, v24
	v_mul_f32_e32 v22, v0, v22
	v_mul_f32_e32 v23, v0, v23
	v_mul_f32_e32 v18, v0, v18

	v_mul_f32_e32 v3, v32, v3
	v_mul_f32_e32 v22, v33, v22
	v_cvt_pk_bf16_f32 v22, v3, v22
	v_mul_f32_e32 v3, v0, v25
	v_mov_b32_e32 v24, v178
	v_mov_b32_e32 v25, v179
	v_mul_f32_e32 v23, v25, v23
	v_mul_f32_e32 v3, v24, v3
	v_cvt_pk_bf16_f32 v23, v3, v23
	v_mov_b32_e32 v24, v180
	v_mov_b32_e32 v25, v181
	v_mul_f32_e32 v3, v0, v20
	v_mul_f32_e32 v3, v24, v3
	v_mul_f32_e32 v18, v25, v18
	v_cvt_pk_bf16_f32 v24, v3, v18
	v_mul_f32_e32 v3, v0, v21
	v_mov_b32_e32 v20, v182
	v_mov_b32_e32 v21, v183
	v_mul_f32_e32 v0, v0, v19
	v_mul_f32_e32 v3, v20, v3
	v_mul_f32_e32 v0, v21, v0
	v_cvt_pk_bf16_f32 v25, v3, v0
	flat_store_dwordx4 v[16:17], v[22:25] offset:3072
	v_lshl_add_u64 v[16:17], s[8:9], 0, v[12:13]
	flat_load_dword v0, v[16:17]
	v_lshl_add_u64 v[12:13], v[12:13], 0, s[18:19]
	s_waitcnt vmcnt(0) lgkmcnt(0)
	v_mul_f32_e32 v3, v0, v0
	ds_bpermute_b32 v3, v26, v3
	s_waitcnt lgkmcnt(0)
	v_fmac_f32_e32 v3, v0, v0
	ds_bpermute_b32 v16, v27, v3
	s_waitcnt lgkmcnt(0)
	v_add_f32_e32 v3, v3, v16
	ds_bpermute_b32 v16, v28, v3
	s_waitcnt lgkmcnt(0)
	v_add_f32_e32 v3, v3, v16
	ds_bpermute_b32 v16, v29, v3
	s_waitcnt lgkmcnt(0)
	v_add_f32_e32 v3, v3, v16
	ds_bpermute_b32 v16, v30, v3
	s_waitcnt lgkmcnt(0)
	v_add_f32_e32 v3, v3, v16
	ds_bpermute_b32 v16, v31, v3
	s_waitcnt lgkmcnt(0)
	v_add_f32_e32 v3, v3, v16
	v_fmamk_f32 v3, v3, 0x3c800000, v207
	v_cmp_gt_f32_e32 vcc, s87, v3
	v_mul_f32_e32 v16, 0x4b800000, v3
	s_nop 0
	v_cndmask_b32_e32 v3, v3, v16, vcc
	v_rsq_f32_e32 v3, v3
	s_nop 0
	v_mul_f32_e32 v16, 0x45800000, v3
	v_cndmask_b32_e32 v3, v3, v16, vcc
	v_mul_f32_e32 v0, v0, v3
	flat_load_dword v3, v[6:7]
	v_lshl_add_u64 v[16:17], s[8:9], 0, v[8:9]
	v_add_co_u32_e32 v18, vcc, s2, v16
	s_mov_b32 s2, 0x1300000
	s_nop 0
	v_addc_co_u32_e32 v19, vcc, 0, v17, vcc
	v_add_co_u32_e32 v16, vcc, s2, v16
	flat_load_dword v18, v[18:19]
	s_nop 0
	v_addc_co_u32_e32 v17, vcc, 0, v17, vcc
	flat_load_dword v16, v[16:17]
	s_movk_i32 s2, 0x3fff
	v_cmp_lt_i32_e32 vcc, s2, v2
	v_lshl_add_u64 v[8:9], v[8:9], 0, s[14:15]
	s_or_b64 s[4:5], vcc, s[4:5]
	s_waitcnt vmcnt(0) lgkmcnt(0)
	v_mul_f32_e32 v0, v3, v0
	ds_bpermute_b32 v3, v31, v0
	s_waitcnt lgkmcnt(0)
	v_mul_f32_e32 v3, v16, v3
	v_cndmask_b32_e64 v3, v3, -v3, s[36:37]
	v_fmac_f32_e32 v3, v18, v0
	v_bfe_u32 v0, v3, 16, 1
	v_add3_u32 v0, v3, v0, s10
	v_lshl_add_u64 v[16:17], s[8:9], 0, v[10:11]
	v_lshl_add_u64 v[10:11], v[10:11], 0, s[14:15]
	flat_store_short_d16_hi v[16:17], v0
	s_andn2_b64 exec, exec, s[4:5]
	s_cbranch_execnz .LBB0_322

.LBB0_381:
	s_and_b64 s[0:1], s[76:77], exec
	s_cselect_b32 s6, s2, s90
	v_mov_b32_e32 v56, v206
	s_lshl_b32 s68, s6, 8
	v_ashrrev_i32_e32 v60, 6, v56
	v_and_b32_e32 v57, 31, v56
	v_lshl_add_u32 v59, v60, 5, s68
	v_or_b32_e32 v198, v59, v57
	v_ashrrev_i32_e32 v199, 31, v198
	v_lshl_add_u64 v[196:197], s[64:65], 0, v[198:199]
	v_mov_b64_e32 v[2:3], s[16:17]
	v_mad_u64_u32 v[2:3], s[0:1], v196, s89, v[2:3]
	v_bfe_u32 v58, v56, 5, 1
	v_mad_i32_i24 v3, v197, s89, v3
	s_lshl_b32 s0, s82, 1
	s_mov_b32 s1, s55
	v_lshl_add_u64 v[4:5], v[2:3], 0, s[0:1]
	v_lshlrev_b32_e32 v0, 4, v58
	v_lshl_add_u64 v[4:5], v[4:5], 0, v[0:1]
	flat_load_dwordx4 v[48:51], v[4:5]
	flat_load_dwordx4 v[44:47], v[4:5] offset:32
	flat_load_dwordx4 v[36:39], v[4:5] offset:64
	flat_load_dwordx4 v[40:43], v[4:5] offset:96
	v_lshl_add_u64 v[2:3], v[2:3], 0, s[54:55]
	v_lshl_add_u64 v[2:3], v[2:3], 0, v[0:1]
	s_movk_i32 s0, 0x1000
	v_add_co_u32_e32 v32, vcc, s0, v2
	v_mov_b64_e32 v[14:15], s[12:13]
	s_nop 0
	v_addc_co_u32_e32 v33, vcc, 0, v3, vcc
	flat_load_dwordx4 v[52:55], v[4:5] offset:128
	flat_load_dwordx4 v[62:65], v[4:5] offset:160
	flat_load_dwordx4 v[66:69], v[4:5] offset:192
	flat_load_dwordx4 v[70:73], v[4:5] offset:224
	s_nop 0
	flat_load_dwordx4 v[2:5], v[32:33]
	flat_load_dwordx4 v[10:13], v[32:33] offset:32
	flat_load_dwordx4 v[6:9], v[32:33] offset:64
	s_nop 0
	flat_load_dwordx4 v[32:35], v[32:33] offset:96
	s_nop 0
	flat_load_dwordx2 v[14:15], v[14:15] sc1
	s_waitcnt vmcnt(0) lgkmcnt(0)
	v_and_b32_e32 v75, 0xffff0000, v49
	v_and_b32_e32 v79, 0xffff0000, v48
	v_and_b32_e32 v78, 0xffff0000, v50
	v_lshlrev_b32_e32 v74, 16, v49
	v_lshlrev_b32_e32 v77, 16, v48
	v_lshlrev_b32_e32 v76, 16, v50
	v_lshlrev_b32_e32 v90, 16, v36
	v_and_b32_e32 v91, 0xffff0000, v36
	v_lshlrev_b32_e32 v92, 16, v37
	v_and_b32_e32 v93, 0xffff0000, v37
	v_lshlrev_b32_e32 v94, 16, v38
	v_and_b32_e32 v96, 0xffff0000, v38
	v_pk_mov_b32 v[36:37], v[38:39], v[42:43] op_sel:[1,0]
	v_lshlrev_b32_e32 v50, 16, v39
	v_mul_f32_e32 v0, v75, v75
	v_pk_mul_f32 v[38:39], v[78:79], v[78:79]
	v_lshlrev_b32_e32 v61, 16, v41
	v_and_b32_e32 v122, 0xffff0000, v41
	v_lshlrev_b32_e32 v41, 16, v43
	v_lshlrev_b32_e32 v95, 16, v40
	v_and_b32_e32 v97, 0xffff0000, v40
	v_mul_f32_e32 v40, v91, v91
	v_mul_f32_e32 v48, v93, v93
	v_pk_fma_f32 v[98:99], v[74:75], v[74:75], v[0:1] op_sel_hi:[1,1,0]
	v_pk_fma_f32 v[38:39], v[76:77], v[76:77], v[38:39]
	v_mul_f32_e32 v102, v61, v61
	v_mul_f32_e32 v103, v122, v122
	v_pk_fma_f32 v[100:101], v[90:91], v[90:91], v[40:41] op_sel_hi:[1,1,0]
	v_pk_fma_f32 v[48:49], v[92:93], v[92:93], v[48:49] op_sel_hi:[1,1,0]
	v_pk_add_f32 v[98:99], v[38:39], v[98:99] op_sel:[1,0] op_sel_hi:[0,1]
	v_and_b32_e32 v85, 0xffff0000, v45
	v_and_b32_e32 v84, 0xffff0000, v44
	v_lshlrev_b32_e32 v87, 16, v47
	v_lshlrev_b32_e32 v86, 16, v46
	v_and_b32_e32 v89, 0xffff0000, v47
	v_and_b32_e32 v88, 0xffff0000, v46
	v_pk_mul_f32 v[46:47], v[96:97], v[96:97]
	v_mov_b32_e32 v101, v102
	v_mov_b32_e32 v49, v103
	v_pk_add_f32 v[38:39], v[38:39], v[98:99]
	v_and_b32_e32 v99, 0xffff0000, v37
	v_and_b32_e32 v98, 0xffff0000, v36
	v_lshlrev_b32_e32 v80, 16, v51
	v_and_b32_e32 v81, 0xffff0000, v51
	v_lshlrev_b32_e32 v83, 16, v45
	v_lshlrev_b32_e32 v82, 16, v44
	v_and_b32_e32 v123, 0xffff0000, v43
	v_lshlrev_b32_e32 v51, 16, v42
	v_pk_mul_f32 v[42:43], v[84:85], v[84:85]
	v_pk_fma_f32 v[46:47], v[94:95], v[94:95], v[46:47]
	v_pk_add_f32 v[48:49], v[100:101], v[48:49]
	v_pk_mul_f32 v[36:37], v[98:99], v[98:99]
	v_pk_mul_f32 v[44:45], v[88:89], v[88:89]
	v_pk_fma_f32 v[42:43], v[82:83], v[82:83], v[42:43]
	v_pk_add_f32 v[46:47], v[46:47], v[48:49]
	v_pk_fma_f32 v[36:37], v[50:51], v[50:51], v[36:37]
	v_mul_f32_e32 v0, v81, v81
	v_pk_fma_f32 v[44:45], v[86:87], v[86:87], v[44:45]
	v_pk_add_f32 v[42:43], v[42:43], v[42:43] op_sel:[0,1] op_sel_hi:[1,0]
	v_pk_add_f32 v[36:37], v[36:37], v[46:47]
	v_pk_fma_f32 v[46:47], v[80:81], v[80:81], v[0:1] op_sel_hi:[1,1,0]
	v_pk_add_f32 v[42:43], v[44:45], v[42:43]
	v_mov_b32_e32 v40, v46
	v_mov_b32_e32 v48, v38
	v_mov_b32_e32 v49, v41
	v_mul_f32_e32 v104, v123, v123
	v_pk_add_f32 v[38:39], v[46:47], v[38:39]
	v_pk_mul_f32 v[46:47], v[40:41], v[48:49]
	v_pk_add_f32 v[42:43], v[44:45], v[42:43] op_sel:[1,0] op_sel_hi:[0,1]
	v_mov_b32_e32 v39, v47
	v_mov_b32_e32 v43, v104
	v_pk_add_f32 v[38:39], v[38:39], v[42:43]
	v_and_b32_e32 v105, 0xffff0000, v53
	v_and_b32_e32 v104, 0xffff0000, v52
	v_readfirstlane_b32 s0, v14
	v_pk_add_f32 v[100:101], v[38:39], v[36:37]
	v_lshlrev_b32_e32 v103, 16, v53
	v_lshlrev_b32_e32 v102, 16, v52
	v_pk_mul_f32 v[36:37], v[104:105], v[104:105]
	v_readfirstlane_b32 s1, v15
	s_add_u32 s0, s0, s18
	v_pk_fma_f32 v[36:37], v[102:103], v[102:103], v[36:37]
	s_addc_u32 s1, s1, s19
	v_lshlrev_b32_e32 v0, 5, v58
	v_pk_add_f32 v[38:39], v[36:37], v[36:37] op_sel:[0,1] op_sel_hi:[1,0]
	v_mov_b64_e32 v[14:15], s[14:15]
	v_lshl_add_u64 v[36:37], s[0:1], 0, v[0:1]
	flat_load_dwordx2 v[14:15], v[14:15] sc1
	v_lshlrev_b32_e32 v107, 16, v55
	flat_load_dwordx2 v[108:109], v[36:37]
	flat_load_dwordx2 v[164:165], v[36:37] offset:8
	flat_load_dwordx2 v[166:167], v[36:37] offset:16
	flat_load_dwordx2 v[168:169], v[36:37] offset:24
	flat_load_dwordx2 v[170:171], v[36:37] offset:64
	flat_load_dwordx2 v[172:173], v[36:37] offset:72
	flat_load_dwordx2 v[174:175], v[36:37] offset:80
	flat_load_dwordx2 v[176:177], v[36:37] offset:88
	flat_load_dwordx2 v[178:179], v[36:37] offset:128
	flat_load_dwordx2 v[180:181], v[36:37] offset:136
	flat_load_dwordx2 v[182:183], v[36:37] offset:144
	flat_load_dwordx2 v[184:185], v[36:37] offset:152
	flat_load_dwordx2 v[186:187], v[36:37] offset:192
	flat_load_dwordx2 v[188:189], v[36:37] offset:200
	flat_load_dwordx2 v[190:191], v[36:37] offset:208
	flat_load_dwordx2 v[192:193], v[36:37] offset:216
	flat_load_dwordx2 v[194:195], v[36:37] offset:256
	flat_load_dwordx2 v[208:209], v[36:37] offset:264
	flat_load_dwordx2 v[210:211], v[36:37] offset:272
	flat_load_dwordx2 v[240:241], v[36:37] offset:280
	flat_load_dwordx2 v[242:243], v[36:37] offset:320
	v_lshlrev_b32_e32 v106, 16, v54
	v_and_b32_e32 v55, 0xffff0000, v55
	v_and_b32_e32 v54, 0xffff0000, v54
	v_pk_mul_f32 v[42:43], v[54:55], v[54:55]
	v_lshlrev_b32_e32 v113, 16, v63
	v_pk_fma_f32 v[42:43], v[106:107], v[106:107], v[42:43]
	v_lshlrev_b32_e32 v112, 16, v62
	v_pk_add_f32 v[38:39], v[42:43], v[38:39]
	v_and_b32_e32 v63, 0xffff0000, v63
	v_and_b32_e32 v62, 0xffff0000, v62
	v_lshlrev_b32_e32 v115, 16, v65
	v_lshlrev_b32_e32 v114, 16, v64
	v_and_b32_e32 v65, 0xffff0000, v65
	v_and_b32_e32 v64, 0xffff0000, v64
	v_and_b32_e32 v121, 0xffff0000, v66
	v_pk_add_f32 v[110:111], v[42:43], v[38:39] op_sel:[1,0] op_sel_hi:[0,1]
	v_pk_mul_f32 v[38:39], v[62:63], v[62:63]
	v_pk_mul_f32 v[42:43], v[64:65], v[64:65]
	v_lshlrev_b32_e32 v120, 16, v66
	v_and_b32_e32 v53, 0xffff0000, v67
	v_mul_f32_e32 v40, v121, v121
	v_pk_fma_f32 v[38:39], v[112:113], v[112:113], v[38:39]
	v_pk_fma_f32 v[116:117], v[114:115], v[114:115], v[42:43]
	v_lshlrev_b32_e32 v52, 16, v67
	v_lshlrev_b32_e32 v124, 16, v71
	v_and_b32_e32 v125, 0xffff0000, v71
	v_pk_fma_f32 v[42:43], v[120:121], v[120:121], v[40:41] op_sel_hi:[1,1,0]
	v_mul_f32_e32 v40, v53, v53
	v_pk_add_f32 v[38:39], v[38:39], v[38:39] op_sel:[0,1] op_sel_hi:[1,0]
	v_mul_f32_e32 v46, v124, v124
	v_mul_f32_e32 v71, v125, v125
	v_and_b32_e32 v45, 0xffff0000, v70
	v_and_b32_e32 v44, 0xffff0000, v68
	v_pk_fma_f32 v[66:67], v[52:53], v[52:53], v[40:41] op_sel_hi:[1,1,0]
	v_pk_add_f32 v[118:119], v[116:117], v[38:39]
	v_lshlrev_b32_e32 v49, 16, v70
	v_lshlrev_b32_e32 v48, 16, v68
	v_pk_mul_f32 v[38:39], v[44:45], v[44:45]
	v_mov_b32_e32 v43, v46
	v_mov_b32_e32 v67, v71
	v_pk_fma_f32 v[38:39], v[48:49], v[48:49], v[38:39]
	v_pk_add_f32 v[42:43], v[42:43], v[66:67]
	v_lshlrev_b32_e32 v47, 16, v73
	v_pk_add_f32 v[66:67], v[38:39], v[42:43]
	v_pk_mov_b32 v[38:39], v[68:69], v[72:73] op_sel:[1,0]
	v_lshlrev_b32_e32 v43, 16, v72
	v_and_b32_e32 v39, 0xffff0000, v39
	v_and_b32_e32 v38, 0xffff0000, v38
	v_lshlrev_b32_e32 v42, 16, v69
	v_pk_mul_f32 v[68:69], v[38:39], v[38:39]
	v_mov_b32_e32 v70, v110
	v_pk_fma_f32 v[68:69], v[42:43], v[42:43], v[68:69]
	v_mov_b32_e32 v71, v47
	v_pk_add_f32 v[66:67], v[68:69], v[66:67]
	v_pk_add_f32 v[68:69], v[100:101], v[100:101] op_sel:[0,1] op_sel_hi:[1,0]
	v_and_b32_e32 v126, 0xffff0000, v73
	v_mov_b32_e32 v46, v68
	v_pk_add_f32 v[68:69], v[68:69], v[110:111]
	v_pk_mul_f32 v[70:71], v[46:47], v[70:71]
	v_mul_f32_e32 v127, v126, v126
	v_mov_b32_e32 v69, v71
	v_pk_add_f32 v[70:71], v[116:117], v[118:119] op_sel:[1,0] op_sel_hi:[0,1]
	v_mov_b32_e32 v71, v127
	v_pk_add_f32 v[68:69], v[68:69], v[70:71]
	s_waitcnt vmcnt(0) lgkmcnt(0)
	v_readfirstlane_b32 s0, v14
	v_pk_add_f32 v[66:67], v[68:69], v[66:67]
	v_readfirstlane_b32 s1, v15
	v_pk_add_f32 v[66:67], v[66:67], v[66:67] op_sel:[0,1] op_sel_hi:[1,0]
	s_add_u32 s0, s0, s40
	v_mov_b32_e32 v40, v66
	s_nop 1
	v_permlane32_swap_b32_e32 v66, v40
	v_add_f32_e32 v40, v66, v40
	v_fmamk_f32 v40, v40, 0x3c000000, v207
	v_mul_f32_e32 v46, 0x4b800000, v40
	v_cmp_gt_f32_e32 vcc, s87, v40
	s_addc_u32 s1, s1, s41
	v_lshlrev_b32_e32 v15, 16, v13
	v_cndmask_b32_e32 v40, v40, v46, vcc
	v_rsq_f32_e32 v40, v40
	v_lshlrev_b32_e32 v14, 16, v35
	v_mul_f32_e32 v46, 0x45800000, v40
	v_cndmask_b32_e32 v40, v40, v46, vcc
	v_mul_f32_e32 v68, 0x3dd53b94, v40
	v_mul_f32_e32 v40, v68, v77
	v_mul_f32_e32 v46, v68, v79
	v_mul_f32_e32 v40, v108, v40
	v_mul_f32_e32 v46, v109, v46
	v_cvt_pk_bf16_f32 v128, v40, v46
	v_mov_b32_e32 v66, v164
	v_mov_b32_e32 v67, v165
	v_mul_f32_e32 v40, v68, v74
	v_mul_f32_e32 v46, v68, v75
	v_mul_f32_e32 v44, v68, v44
	v_mul_f32_e32 v42, v68, v42
	v_mul_f32_e32 v38, v68, v38
	v_mul_f32_e32 v39, v68, v39
	v_mul_f32_e32 v40, v66, v40
	v_mul_f32_e32 v46, v67, v46
	v_cvt_pk_bf16_f32 v129, v40, v46
	v_mov_b32_e32 v66, v166
	v_mov_b32_e32 v67, v167
	v_mul_f32_e32 v40, v68, v76
	v_mul_f32_e32 v46, v68, v78
	v_mul_f32_e32 v40, v40, v66
	v_mul_f32_e32 v46, v46, v67
	v_cvt_pk_bf16_f32 v130, v40, v46
	v_mov_b32_e32 v66, v168
	v_mov_b32_e32 v67, v169
	v_mul_f32_e32 v40, v68, v80
	v_mul_f32_e32 v46, v68, v81
	v_mul_f32_e32 v40, v40, v66
	v_mul_f32_e32 v46, v46, v67
	v_cvt_pk_bf16_f32 v131, v40, v46
	v_mov_b32_e32 v66, v170
	v_mov_b32_e32 v67, v171
	v_mul_f32_e32 v40, v68, v82
	v_mul_f32_e32 v46, v68, v84
	v_lshlrev_b32_e32 v82, 16, v8
	v_and_b32_e32 v84, 0xffff0000, v8
	v_mov_b32_e32 v162, v84
	v_mov_b32_e32 v160, v82
	v_mul_f32_e32 v40, v40, v66
	v_mul_f32_e32 v46, v46, v67
	v_cvt_pk_bf16_f32 v132, v40, v46
	v_mov_b32_e32 v66, v172
	v_mov_b32_e32 v67, v173
	v_mul_f32_e32 v40, v68, v83
	v_mul_f32_e32 v46, v68, v85
	v_lshlrev_b32_e32 v83, 16, v4
	v_and_b32_e32 v85, 0xffff0000, v4
	v_mov_b32_e32 v111, v83
	v_mul_f32_e32 v40, v40, v66
	v_mul_f32_e32 v46, v46, v67
	v_cvt_pk_bf16_f32 v133, v40, v46
	v_mov_b32_e32 v66, v174
	v_mov_b32_e32 v67, v175
	v_mul_f32_e32 v40, v68, v86
	v_mul_f32_e32 v46, v68, v88
	v_lshlrev_b32_e32 v86, 16, v7
	v_and_b32_e32 v88, 0xffff0000, v7
	v_mul_f32_e32 v40, v40, v66
	v_mul_f32_e32 v46, v46, v67
	v_cvt_pk_bf16_f32 v134, v40, v46
	v_mov_b32_e32 v66, v176
	v_mov_b32_e32 v67, v177
	v_mul_f32_e32 v40, v68, v87
	v_mul_f32_e32 v46, v68, v89
	v_lshlrev_b32_e32 v87, 16, v3
	v_and_b32_e32 v89, 0xffff0000, v3
	v_mov_b32_e32 v119, v87
	v_mul_f32_e32 v40, v40, v66
	v_mul_f32_e32 v46, v46, v67
	v_cvt_pk_bf16_f32 v135, v40, v46
	v_mov_b32_e32 v66, v178
	v_mov_b32_e32 v67, v179
	v_mul_f32_e32 v40, v68, v90
	v_mul_f32_e32 v46, v68, v91
	v_lshlrev_b32_e32 v91, 16, v2
	v_lshlrev_b32_e32 v90, 16, v6
	v_mov_b32_e32 v116, v90
	v_mov_b32_e32 v118, v91
	v_mul_f32_e32 v40, v40, v66
	v_mul_f32_e32 v46, v46, v67
	v_cvt_pk_bf16_f32 v136, v40, v46
	v_mov_b32_e32 v66, v180
	v_mov_b32_e32 v67, v181
	v_mul_f32_e32 v40, v68, v92
	v_mul_f32_e32 v46, v68, v93
	v_and_b32_e32 v93, 0xffff0000, v2
	v_mul_f32_e32 v2, v68, v126
	v_and_b32_e32 v92, 0xffff0000, v6
	v_mov_b32_e32 v117, v92
	v_mul_f32_e32 v40, v40, v66
	v_mul_f32_e32 v46, v46, v67
	v_cvt_pk_bf16_f32 v137, v40, v46
	v_mov_b32_e32 v66, v182
	v_mov_b32_e32 v67, v183
	v_mul_f32_e32 v40, v68, v94
	v_mul_f32_e32 v46, v68, v96
	v_mul_f32_e32 v40, v40, v66
	v_mul_f32_e32 v46, v46, v67
	v_cvt_pk_bf16_f32 v138, v40, v46
	v_mov_b32_e32 v66, v184
	v_mov_b32_e32 v67, v185
	v_mul_f32_e32 v40, v68, v50
	v_mul_f32_e32 v46, v68, v98
	v_mov_b32_e32 v98, v15
	v_mul_f32_e32 v40, v40, v66
	v_mul_f32_e32 v46, v46, v67
	v_cvt_pk_bf16_f32 v139, v40, v46
	v_mov_b32_e32 v66, v186
	v_mov_b32_e32 v67, v187
	v_mul_f32_e32 v40, v68, v95
	v_mul_f32_e32 v46, v68, v97
	v_pk_mul_f32 v[94:95], v[14:15], v[14:15]
	v_mul_f32_e32 v40, v40, v66
	v_mul_f32_e32 v46, v46, v67
	v_cvt_pk_bf16_f32 v140, v40, v46
	v_mov_b32_e32 v66, v188
	v_mov_b32_e32 v67, v189
	v_mul_f32_e32 v40, v68, v61
	v_mul_f32_e32 v46, v68, v122
	v_mul_f32_e32 v122, v92, v92
	v_pk_fma_f32 v[116:117], v[116:117], v[116:117], v[122:123] op_sel_hi:[1,1,0]
	v_mul_f32_e32 v40, v40, v66
	v_mul_f32_e32 v46, v46, v67
	v_cvt_pk_bf16_f32 v141, v40, v46
	v_mov_b32_e32 v66, v190
	v_mov_b32_e32 v67, v191
	v_mul_f32_e32 v40, v68, v51
	v_mul_f32_e32 v46, v68, v99
	v_mul_f32_e32 v40, v40, v66
	v_mul_f32_e32 v46, v46, v67
	v_cvt_pk_bf16_f32 v142, v40, v46
	v_mov_b32_e32 v50, v192
	v_mov_b32_e32 v51, v193
	v_mul_f32_e32 v40, v68, v41
	v_mul_f32_e32 v41, v68, v123
	v_mul_f32_e32 v46, v68, v102
	v_mul_f32_e32 v40, v40, v50
	v_mul_f32_e32 v41, v41, v51
	v_cvt_pk_bf16_f32 v143, v40, v41
	v_mov_b32_e32 v40, v194
	v_mov_b32_e32 v41, v195
	v_mul_f32_e32 v50, v68, v104
	v_mul_f32_e32 v40, v46, v40
	v_mul_f32_e32 v41, v50, v41
	v_cvt_pk_bf16_f32 v144, v40, v41
	v_mov_b32_e32 v40, v208
	v_mov_b32_e32 v41, v209
	v_mul_f32_e32 v46, v68, v103
	v_mul_f32_e32 v50, v68, v105
	v_mul_f32_e32 v40, v46, v40
	v_mul_f32_e32 v41, v50, v41
	v_cvt_pk_bf16_f32 v145, v40, v41
	v_mov_b32_e32 v40, v210
	v_mov_b32_e32 v41, v211
	v_mul_f32_e32 v46, v68, v106
	v_mul_f32_e32 v50, v68, v54
	v_lshlrev_b32_e32 v54, 16, v9
	v_mul_f32_e32 v40, v46, v40
	v_mul_f32_e32 v41, v50, v41
	v_cvt_pk_bf16_f32 v146, v40, v41
	v_mov_b32_e32 v40, v240
	v_mov_b32_e32 v41, v241
	v_mul_f32_e32 v46, v68, v107
	v_mul_f32_e32 v50, v68, v55
	v_lshlrev_b32_e32 v55, 16, v5
	v_mov_b32_e32 v110, v55
	v_mul_f32_e32 v40, v46, v40
	v_mul_f32_e32 v41, v50, v41
	v_cvt_pk_bf16_f32 v147, v40, v41
	v_mov_b32_e32 v40, v242
	v_mov_b32_e32 v41, v243
	v_mul_f32_e32 v46, v68, v112
	v_mul_f32_e32 v50, v68, v62
	v_mul_f32_e32 v40, v46, v40
	v_mul_f32_e32 v41, v50, v41
	v_cvt_pk_bf16_f32 v148, v40, v41
	flat_load_dwordx2 v[40:41], v[36:37] offset:328
	flat_load_dwordx2 v[164:165], v[36:37] offset:336
	flat_load_dwordx2 v[166:167], v[36:37] offset:344
	flat_load_dwordx2 v[168:169], v[36:37] offset:384
	flat_load_dwordx2 v[170:171], v[36:37] offset:392
	flat_load_dwordx2 v[172:173], v[36:37] offset:400
	flat_load_dwordx2 v[174:175], v[36:37] offset:408
	flat_load_dwordx2 v[176:177], v[36:37] offset:448
	flat_load_dwordx2 v[178:179], v[36:37] offset:456
	flat_load_dwordx2 v[180:181], v[36:37] offset:464
	flat_load_dwordx2 v[182:183], v[36:37] offset:472
	v_mul_f32_e32 v46, v68, v113
	v_mul_f32_e32 v50, v68, v63
	v_mov_b32_e32 v113, v85
	s_waitcnt vmcnt(0) lgkmcnt(0)
	v_mul_f32_e32 v40, v46, v40
	v_mul_f32_e32 v41, v50, v41
	v_cvt_pk_bf16_f32 v149, v40, v41
	v_mov_b32_e32 v40, v164
	v_mov_b32_e32 v41, v165
	v_mul_f32_e32 v46, v68, v114
	v_mul_f32_e32 v50, v68, v64
	v_mov_b32_e32 v114, v86
	v_mul_f32_e32 v40, v46, v40
	v_mul_f32_e32 v41, v50, v41
	v_cvt_pk_bf16_f32 v150, v40, v41
	v_mov_b32_e32 v40, v166
	v_mov_b32_e32 v41, v167
	v_mul_f32_e32 v46, v68, v115
	v_mul_f32_e32 v50, v68, v65
	v_mov_b32_e32 v115, v88
	v_mul_f32_e32 v40, v46, v40
	v_mul_f32_e32 v41, v50, v41
	v_cvt_pk_bf16_f32 v151, v40, v41
	v_mov_b32_e32 v40, v168
	v_mov_b32_e32 v41, v169
	v_mul_f32_e32 v46, v68, v120
	v_mul_f32_e32 v50, v68, v121
	v_mov_b32_e32 v120, v93
	v_mov_b32_e32 v121, v89
	v_pk_mul_f32 v[120:121], v[120:121], v[120:121]
	v_mul_f32_e32 v40, v46, v40
	v_mul_f32_e32 v41, v50, v41
	v_cvt_pk_bf16_f32 v152, v40, v41
	v_mov_b32_e32 v40, v170
	v_mov_b32_e32 v41, v171
	v_mul_f32_e32 v46, v68, v52
	v_mul_f32_e32 v50, v68, v53
	v_and_b32_e32 v53, 0xffff0000, v5
	v_and_b32_e32 v52, 0xffff0000, v9
	v_mov_b32_e32 v112, v53
	v_pk_mul_f32 v[112:113], v[112:113], v[112:113]
	v_mov_b32_e32 v126, v52
	v_mul_f32_e32 v40, v46, v40
	v_mul_f32_e32 v41, v50, v41
	v_cvt_pk_bf16_f32 v153, v40, v41
	v_mov_b32_e32 v40, v172
	v_mov_b32_e32 v41, v173
	v_mul_f32_e32 v46, v68, v48
	v_lshlrev_b64 v[50:51], 5, v[196:197]
	v_mul_f32_e32 v40, v46, v40
	v_mul_f32_e32 v41, v44, v41
	v_cvt_pk_bf16_f32 v154, v40, v41
	v_mov_b32_e32 v40, v174
	v_mov_b32_e32 v41, v175
	v_lshlrev_b32_e32 v46, 3, v58
	v_or_b32_e32 v50, v50, v46
	v_lshlrev_b32_e32 v44, 16, v32
	v_and_b32_e32 v32, 0xffff0000, v32
	v_mov_b32_e32 v163, v32
	v_mov_b32_e32 v161, v44
	v_mul_f32_e32 v40, v42, v40
	v_mul_f32_e32 v38, v38, v41
	v_cvt_pk_bf16_f32 v155, v40, v38
	v_mov_b32_e32 v40, v176
	v_mov_b32_e32 v41, v177
	v_mul_f32_e32 v38, v68, v49
	v_mul_f32_e32 v42, v68, v45
	v_lshl_add_u64 v[48:49], s[0:1], 0, v[0:1]
	v_mul_f32_e32 v0, v68, v47
	v_lshlrev_b32_e32 v45, 16, v10
	v_mov_b32_e32 v106, v45
	v_mul_f32_e32 v38, v38, v40
	v_mul_f32_e32 v40, v42, v41
	v_cvt_pk_bf16_f32 v156, v38, v40
	v_mov_b32_e32 v40, v178
	v_mov_b32_e32 v41, v179
	v_mul_f32_e32 v38, v68, v124
	v_mul_f32_e32 v42, v68, v125
	v_mov_b32_e32 v124, v54
	v_mul_f32_e32 v38, v38, v40
	v_mul_f32_e32 v40, v42, v41
	v_cvt_pk_bf16_f32 v157, v38, v40
	v_mov_b32_e32 v40, v180
	v_mov_b32_e32 v41, v181
	v_mul_f32_e32 v38, v68, v43
	v_and_b32_e32 v43, 0xffff0000, v11
	v_and_b32_e32 v42, 0xffff0000, v33
	v_mov_b32_e32 v109, v43
	v_pk_mul_f32 v[104:105], v[42:43], v[42:43]
	v_mul_f32_e32 v38, v38, v40
	v_mul_f32_e32 v39, v39, v41
	v_cvt_pk_bf16_f32 v158, v38, v39
	v_mov_b32_e32 v62, v182
	v_mov_b32_e32 v63, v183
	v_lshlrev_b64 v[36:37], 2, v[50:51]
	v_lshl_add_u64 v[74:75], s[46:47], 0, v[36:37]
	v_lshl_add_u64 v[78:79], s[48:49], 0, v[36:37]
	v_or_b32_e32 v36, 16, v36
	v_lshl_add_u64 v[76:77], s[46:47], 0, v[36:37]
	v_lshl_add_u64 v[80:81], s[48:49], 0, v[36:37]
	v_and_b32_e32 v37, 0xffff0000, v13
	v_and_b32_e32 v36, 0xffff0000, v35
	v_lshlrev_b32_e32 v39, 16, v12
	v_and_b32_e32 v35, 0xffff0000, v12
	v_lshlrev_b32_e32 v41, 16, v11
	v_lshlrev_b32_e32 v40, 16, v33
	v_and_b32_e32 v33, 0xffff0000, v10
	v_mov_b32_e32 v100, v37
	v_mov_b32_e32 v101, v35
	v_mov_b32_e32 v108, v33
	v_mov_b32_e32 v99, v39
	v_mov_b32_e32 v107, v41
	v_pk_mul_f32 v[100:101], v[100:101], v[100:101]
	v_pk_mul_f32 v[108:109], v[108:109], v[108:109]
	v_lshlrev_b32_e32 v38, 16, v34
	v_and_b32_e32 v34, 0xffff0000, v34
	v_pk_mul_f32 v[102:103], v[40:41], v[40:41]
	v_pk_fma_f32 v[98:99], v[98:99], v[98:99], v[100:101]
	v_pk_fma_f32 v[100:101], v[106:107], v[106:107], v[108:109]
	v_pk_fma_f32 v[108:109], v[118:119], v[118:119], v[120:121]
	v_mov_b32_e32 v127, v34
	v_pk_fma_f32 v[106:107], v[110:111], v[110:111], v[112:113]
	v_mov_b32_e32 v117, v102
	v_pk_add_f32 v[100:101], v[100:101], v[100:101] op_sel:[0,1] op_sel_hi:[1,0]
	v_pk_add_f32 v[102:103], v[108:109], v[108:109] op_sel:[0,1] op_sel_hi:[1,0]
	v_pk_mul_f32 v[122:123], v[126:127], v[126:127]
	v_pk_mul_f32 v[126:127], v[162:163], v[162:163]
	v_pk_add_f32 v[100:101], v[98:99], v[100:101] op_sel:[1,0] op_sel_hi:[0,1]
	v_pk_add_f32 v[102:103], v[106:107], v[102:103] op_sel:[1,0] op_sel_hi:[0,1]
	v_pk_mul_f32 v[96:97], v[36:37], v[36:37]
	v_mov_b32_e32 v125, v38
	v_pk_fma_f32 v[112:113], v[160:161], v[160:161], v[126:127]
	v_pk_add_f32 v[98:99], v[98:99], v[100:101]
	v_pk_add_f32 v[100:101], v[106:107], v[102:103]
	v_pk_fma_f32 v[110:111], v[124:125], v[124:125], v[122:123]
	v_mov_b32_e32 v101, v94
	v_mov_b32_e32 v99, v96
	v_pk_add_f32 v[94:95], v[100:101], v[98:99]
	v_or_b32_e32 v50, 16, v50
	v_mul_f32_e32 v2, v2, v63
	v_mul_f32_e32 v0, v0, v62
	v_cvt_pk_bf16_f32 v159, v0, v2
	flat_load_dwordx4 v[62:65], v[48:49] offset:128
	flat_load_dwordx4 v[66:69], v[48:49] offset:144
	flat_load_dwordx4 v[70:73], v[48:49]
	flat_load_dwordx4 v[10:13], v[48:49] offset:16
	flat_load_dwordx4 v[6:9], v[76:77]
	flat_load_dwordx4 v[2:5], v[80:81]
	s_nop 0
	flat_load_dwordx4 v[74:77], v[74:75]
	s_nop 0
	flat_load_dwordx4 v[78:81], v[78:79]
	v_mul_f32_e32 v0, v88, v88
	v_pk_fma_f32 v[114:115], v[114:115], v[114:115], v[0:1] op_sel_hi:[1,1,0]
	s_waitcnt vmcnt(0) lgkmcnt(0)
	v_mov_b32_e32 v106, v64
	v_mov_b32_e32 v115, v104
	v_pk_add_f32 v[104:105], v[116:117], v[114:115]
	v_mov_b32_e32 v98, v68
	v_pk_add_f32 v[104:105], v[112:113], v[104:105]
	v_mov_b32_e32 v99, v12
	v_pk_add_f32 v[102:103], v[110:111], v[104:105]
	v_mov_b32_e32 v107, v72
	v_pk_add_f32 v[94:95], v[94:95], v[102:103]
	v_mov_b32_e32 v102, v66
	v_pk_add_f32 v[94:95], v[94:95], v[94:95] op_sel:[0,1] op_sel_hi:[1,0]
	v_mov_b32_e32 v103, v10
	v_mov_b32_e32 v0, v94
	s_nop 1
	v_permlane32_swap_b32_e32 v94, v0
	v_add_f32_e32 v0, v94, v0
	v_fmamk_f32 v0, v0, 0x3c800000, v207
	v_mul_f32_e32 v47, 0x4b800000, v0
	v_cmp_gt_f32_e32 vcc, s87, v0
	v_mov_b32_e32 v110, v62
	v_mov_b32_e32 v111, v70
	v_cndmask_b32_e32 v0, v0, v47, vcc
	v_rsq_f32_e32 v0, v0
	v_mov_b32_e32 v70, v63
	v_mov_b32_e32 v72, v65
	v_mov_b32_e32 v10, v67
	v_mul_f32_e32 v47, 0x45800000, v0
	v_cndmask_b32_e32 v0, v0, v47, vcc
	v_pk_mul_f32 v[90:91], v[0:1], v[90:91] op_sel_hi:[0,1]
	v_pk_mul_f32 v[92:93], v[0:1], v[92:93] op_sel_hi:[0,1]
	v_pk_mul_f32 v[86:87], v[0:1], v[86:87] op_sel_hi:[0,1]
	v_pk_mul_f32 v[88:89], v[0:1], v[88:89] op_sel_hi:[0,1]
	v_pk_mul_f32 v[82:83], v[0:1], v[82:83] op_sel_hi:[0,1]
	v_pk_mul_f32 v[84:85], v[0:1], v[84:85] op_sel_hi:[0,1]
	v_pk_mul_f32 v[54:55], v[0:1], v[54:55] op_sel_hi:[0,1]
	v_pk_mul_f32 v[52:53], v[0:1], v[52:53] op_sel_hi:[0,1]
	v_mov_b32_e32 v12, v69
	v_mov_b32_e32 v100, v8
	v_mov_b32_e32 v101, v4
	v_mov_b32_e32 v104, v6
	v_mov_b32_e32 v105, v2
	v_mov_b32_e32 v108, v76
	v_mov_b32_e32 v109, v80
	v_mov_b32_e32 v112, v74
	v_mov_b32_e32 v113, v78
	v_mov_b32_e32 v114, v78
	v_mov_b32_e32 v115, v74
	v_mov_b32_e32 v74, v79
	v_mov_b32_e32 v78, v75
	v_mov_b32_e32 v62, v80
	v_mov_b32_e32 v63, v76
	v_mov_b32_e32 v76, v81
	v_mov_b32_e32 v80, v77
	v_mov_b32_e32 v64, v2
	v_mov_b32_e32 v65, v6
	v_mov_b32_e32 v6, v3
	v_mov_b32_e32 v2, v7
	v_mov_b32_e32 v66, v4
	v_mov_b32_e32 v67, v8
	v_mov_b32_e32 v8, v5
	v_pk_mul_f32 v[68:69], v[90:91], v[110:111]
	v_pk_mul_f32 v[70:71], v[92:93], v[70:71]
	v_pk_mul_f32 v[86:87], v[86:87], v[106:107]
	v_pk_mul_f32 v[72:73], v[88:89], v[72:73]
	v_pk_mul_f32 v[82:83], v[82:83], v[102:103]
	v_pk_mul_f32 v[10:11], v[84:85], v[10:11]
	v_pk_mul_f32 v[54:55], v[54:55], v[98:99]
	v_pk_mul_f32 v[12:13], v[52:53], v[12:13]
	v_mov_b32_e32 v4, v9
	v_pk_mul_f32 v[52:53], v[68:69], v[114:115]
	v_pk_mul_f32 v[68:69], v[68:69], v[112:113]
	v_pk_mul_f32 v[74:75], v[70:71], v[74:75]
	v_pk_mul_f32 v[70:71], v[70:71], v[78:79]
	v_pk_mul_f32 v[62:63], v[86:87], v[62:63]
	v_pk_mul_f32 v[78:79], v[86:87], v[108:109]
	v_pk_mul_f32 v[76:77], v[72:73], v[76:77]
	v_pk_mul_f32 v[72:73], v[72:73], v[80:81]
	v_pk_mul_f32 v[64:65], v[82:83], v[64:65]
	v_pk_mul_f32 v[6:7], v[10:11], v[6:7]
	v_pk_mul_f32 v[2:3], v[10:11], v[2:3]
	v_pk_mul_f32 v[10:11], v[54:55], v[66:67]
	v_pk_mul_f32 v[54:55], v[54:55], v[100:101]
	v_pk_mul_f32 v[8:9], v[12:13], v[8:9]
	v_lshlrev_b64 v[94:95], 2, v[50:51]
	v_pk_mul_f32 v[80:81], v[82:83], v[104:105]
	v_pk_mul_f32 v[4:5], v[12:13], v[4:5]
	v_sub_f32_e32 v12, v53, v52
	v_add_f32_e32 v13, v68, v69
	v_sub_f32_e32 v47, v75, v74
	v_add_f32_e32 v52, v70, v71
	v_sub_f32_e32 v53, v63, v62
	v_add_f32_e32 v61, v78, v79
	v_add_f32_e32 v63, v72, v73
	v_sub_f32_e32 v64, v65, v64
	v_sub_f32_e32 v6, v7, v6
	v_add_f32_e32 v7, v54, v55
	v_sub_f32_e32 v8, v9, v8
	v_lshl_add_u64 v[50:51], s[48:49], 0, v[94:95]
	v_sub_f32_e32 v62, v77, v76
	v_add_f32_e32 v65, v80, v81
	v_add_f32_e32 v2, v2, v3
	v_sub_f32_e32 v3, v11, v10
	v_add_f32_e32 v4, v4, v5
	v_mul_f32_e32 v5, 0x3dd53b94, v12
	v_mul_f32_e32 v9, 0x3dd53b94, v13
	v_mul_f32_e32 v10, 0x3dd53b94, v47
	v_mul_f32_e32 v11, 0x3dd53b94, v52
	v_mul_f32_e32 v12, 0x3dd53b94, v53
	v_mul_f32_e32 v13, 0x3dd53b94, v61
	v_mul_f32_e32 v52, 0x3dd53b94, v63
	v_mul_f32_e32 v53, 0x3dd53b94, v64
	v_mul_f32_e32 v6, 0x3dd53b94, v6
	v_mul_f32_e32 v7, 0x3dd53b94, v7
	v_mul_f32_e32 v8, 0x3dd53b94, v8
	v_lshl_add_u64 v[96:97], s[46:47], 0, v[94:95]
	v_mul_f32_e32 v47, 0x3dd53b94, v62
	v_mul_f32_e32 v54, 0x3dd53b94, v65
	v_mul_f32_e32 v2, 0x3dd53b94, v2
	v_mul_f32_e32 v3, 0x3dd53b94, v3
	v_mul_f32_e32 v4, 0x3dd53b94, v4
	v_cvt_pk_bf16_f32 v160, v5, v10
	v_cvt_pk_bf16_f32 v161, v12, v47
	v_cvt_pk_bf16_f32 v162, v53, v6
	v_cvt_pk_bf16_f32 v163, v3, v8
	v_cvt_pk_bf16_f32 v164, v9, v11
	v_cvt_pk_bf16_f32 v165, v13, v52
	v_cvt_pk_bf16_f32 v166, v54, v2
	v_cvt_pk_bf16_f32 v167, v7, v4
	flat_load_dwordx4 v[6:9], v[48:49] offset:192
	flat_load_dwordx4 v[10:13], v[48:49] offset:64
	s_nop 0
	flat_load_dwordx4 v[50:53], v[50:51]
	s_nop 0
	flat_load_dwordx4 v[62:65], v[96:97]
	v_or_b32_e32 v94, 16, v94
	v_lshl_add_u64 v[2:3], s[46:47], 0, v[94:95]
	v_lshl_add_u64 v[4:5], s[48:49], 0, v[94:95]
	flat_load_dwordx4 v[66:69], v[48:49] offset:208
	flat_load_dwordx4 v[70:73], v[48:49] offset:80
	flat_load_dwordx4 v[74:77], v[4:5]
	flat_load_dwordx4 v[78:81], v[2:3]
	v_mul_hi_i32 v2, v56, s81
	v_lshrrev_b32_e32 v3, 31, v2
	v_ashrrev_i32_e32 v2, 2, v2
	v_pk_mul_f32 v[44:45], v[0:1], v[44:45] op_sel_hi:[0,1]
	v_add_u32_e32 v3, v2, v3
	v_pk_mul_f32 v[32:33], v[0:1], v[32:33] op_sel_hi:[0,1]
	v_pk_mul_f32 v[40:41], v[0:1], v[40:41] op_sel_hi:[0,1]
	v_pk_mul_f32 v[42:43], v[0:1], v[42:43] op_sel_hi:[0,1]
	v_pk_mul_f32 v[38:39], v[0:1], v[38:39] op_sel_hi:[0,1]
	v_pk_mul_f32 v[34:35], v[0:1], v[34:35] op_sel_hi:[0,1]
	v_pk_mul_f32 v[14:15], v[0:1], v[14:15] op_sel_hi:[0,1]
	v_pk_mul_f32 v[36:37], v[0:1], v[36:37] op_sel_hi:[0,1]
	v_mul_lo_u32 v2, v3, 24
	v_sub_u32_e32 v2, v56, v2
	v_lshlrev_b32_e32 v5, 3, v2
	v_cmp_lt_i32_e32 vcc, 15, v2
	s_waitcnt vmcnt(0) lgkmcnt(0)
	v_mov_b32_e32 v48, v6
	v_mov_b32_e32 v49, v10
	v_mov_b32_e32 v54, v50
	v_mov_b32_e32 v55, v62
	v_mov_b32_e32 v10, v7
	v_mov_b32_e32 v6, v8
	v_mov_b32_e32 v7, v12
	v_mov_b32_e32 v12, v9
	v_mov_b32_e32 v8, v66
	v_mov_b32_e32 v9, v70
	v_mov_b32_e32 v70, v67
	v_mov_b32_e32 v66, v68
	v_mov_b32_e32 v67, v72
	v_mov_b32_e32 v72, v69
	v_pk_mul_f32 v[44:45], v[44:45], v[48:49]
	v_mov_b32_e32 v82, v62
	v_mov_b32_e32 v83, v50
	v_mov_b32_e32 v62, v51
	v_mov_b32_e32 v50, v63
	v_mov_b32_e32 v84, v52
	v_mov_b32_e32 v85, v64
	v_mov_b32_e32 v86, v64
	v_mov_b32_e32 v87, v52
	v_mov_b32_e32 v64, v53
	v_mov_b32_e32 v52, v65
	v_mov_b32_e32 v88, v74
	v_mov_b32_e32 v89, v78
	v_mov_b32_e32 v90, v78
	v_mov_b32_e32 v91, v74
	v_mov_b32_e32 v78, v75
	v_mov_b32_e32 v74, v79
	v_mov_b32_e32 v92, v76
	v_mov_b32_e32 v93, v80
	v_mov_b32_e32 v94, v80
	v_mov_b32_e32 v95, v76
	v_mov_b32_e32 v80, v77
	v_mov_b32_e32 v76, v81
	v_pk_mul_f32 v[10:11], v[32:33], v[10:11]
	v_pk_mul_f32 v[6:7], v[40:41], v[6:7]
	v_pk_mul_f32 v[12:13], v[42:43], v[12:13]
	v_pk_mul_f32 v[8:9], v[38:39], v[8:9]
	v_pk_mul_f32 v[32:33], v[34:35], v[70:71]
	v_pk_mul_f32 v[14:15], v[14:15], v[66:67]
	v_pk_mul_f32 v[34:35], v[36:37], v[72:73]
	v_pk_mul_f32 v[36:37], v[44:45], v[54:55]
	v_pk_mul_f32 v[38:39], v[44:45], v[82:83]
	v_pk_mul_f32 v[40:41], v[10:11], v[62:63]
	v_pk_mul_f32 v[10:11], v[10:11], v[50:51]
	v_pk_mul_f32 v[42:43], v[6:7], v[84:85]
	v_pk_mul_f32 v[6:7], v[6:7], v[86:87]
	v_pk_mul_f32 v[44:45], v[12:13], v[64:65]
	v_pk_mul_f32 v[12:13], v[12:13], v[52:53]
	v_pk_mul_f32 v[48:49], v[8:9], v[88:89]
	v_pk_mul_f32 v[8:9], v[8:9], v[90:91]
	v_pk_mul_f32 v[50:51], v[32:33], v[78:79]
	v_pk_mul_f32 v[32:33], v[32:33], v[74:75]
	v_pk_mul_f32 v[52:53], v[14:15], v[92:93]
	v_pk_mul_f32 v[14:15], v[14:15], v[94:95]
	v_pk_mul_f32 v[54:55], v[34:35], v[80:81]
	v_pk_mul_f32 v[34:35], v[34:35], v[76:77]
	v_sub_f32_e32 v0, v37, v36
	v_add_f32_e32 v4, v38, v39
	v_sub_f32_e32 v36, v41, v40
	v_add_f32_e32 v10, v10, v11
	v_sub_f32_e32 v11, v43, v42
	v_add_f32_e32 v6, v6, v7
	v_sub_f32_e32 v7, v45, v44
	v_add_f32_e32 v12, v12, v13
	v_sub_f32_e32 v13, v49, v48
	v_add_f32_e32 v8, v8, v9
	v_sub_f32_e32 v9, v51, v50
	v_add_f32_e32 v32, v32, v33
	v_sub_f32_e32 v33, v53, v52
	v_add_f32_e32 v14, v14, v15
	v_sub_f32_e32 v15, v55, v54
	v_add_f32_e32 v34, v34, v35
	v_mul_f32_e32 v0, 0x3dd53b94, v0
	v_mul_f32_e32 v4, 0x3dd53b94, v4
	v_mul_f32_e32 v35, 0x3dd53b94, v36
	v_mul_f32_e32 v10, 0x3dd53b94, v10
	v_mul_f32_e32 v11, 0x3dd53b94, v11
	v_mul_f32_e32 v6, 0x3dd53b94, v6
	v_mul_f32_e32 v7, 0x3dd53b94, v7
	v_mul_f32_e32 v12, 0x3dd53b94, v12
	v_mul_f32_e32 v13, 0x3dd53b94, v13
	v_mul_f32_e32 v8, 0x3dd53b94, v8
	v_mul_f32_e32 v9, 0x3dd53b94, v9
	v_mul_f32_e32 v32, 0x3dd53b94, v32
	v_mul_f32_e32 v33, 0x3dd53b94, v33
	v_mul_f32_e32 v14, 0x3dd53b94, v14
	v_mul_f32_e32 v15, 0x3dd53b94, v15
	v_mul_f32_e32 v34, 0x3dd53b94, v34
	v_cvt_pk_bf16_f32 v168, v0, v35
	v_cvt_pk_bf16_f32 v169, v11, v7
	v_cvt_pk_bf16_f32 v170, v13, v9
	v_cvt_pk_bf16_f32 v171, v33, v15
	v_cvt_pk_bf16_f32 v172, v4, v10
	v_cvt_pk_bf16_f32 v173, v6, v12
	v_cvt_pk_bf16_f32 v174, v8, v32
	v_cvt_pk_bf16_f32 v175, v14, v34
	s_and_saveexec_b64 s[0:1], vcc
	s_xor_b64 s[0:1], exec, s[0:1]
	v_lshl_add_u32 v0, v3, 6, v5
	v_sub_u32_e32 v0, 0x7f, v0
	s_andn2_saveexec_b64 s[0:1], s[0:1]
	v_lshl_or_b32 v0, v3, 11, s82
	v_add_u32_e32 v0, v0, v5
	s_or_b64 exec, exec, s[0:1]
	v_add_u32_e32 v2, 0x200, v56
	v_mul_hi_i32 v4, v2, s81
	v_lshrrev_b32_e32 v6, 31, v4
	v_ashrrev_i32_e32 v4, 2, v4
	v_add_u32_e32 v6, v4, v6
	v_mul_lo_u32 v4, v6, 24
	v_sub_u32_e32 v2, v2, v4
	v_lshlrev_b32_e32 v7, 3, v2
	v_cmp_lt_i32_e32 vcc, 15, v2
	s_and_saveexec_b64 s[0:1], vcc
	s_xor_b64 s[0:1], exec, s[0:1]
	v_lshl_add_u32 v2, v6, 6, v7
	v_sub_u32_e32 v2, 0x7f, v2
	s_andn2_saveexec_b64 s[0:1], s[0:1]
	v_lshl_or_b32 v2, v6, 11, s82
	v_add_u32_e32 v2, v2, v7
	s_or_b64 exec, exec, s[0:1]
	v_add_u32_e32 v4, 0x400, v56
	v_mul_hi_i32 v8, v4, s81
	v_lshrrev_b32_e32 v9, 31, v8
	v_ashrrev_i32_e32 v8, 2, v8
	v_add_u32_e32 v8, v8, v9
	v_mul_lo_u32 v9, v8, 24
	v_sub_u32_e32 v4, v4, v9
	v_lshlrev_b32_e32 v9, 3, v4
	v_cmp_lt_i32_e32 vcc, 15, v4
	s_and_saveexec_b64 s[0:1], vcc
	s_xor_b64 s[0:1], exec, s[0:1]
	v_lshl_add_u32 v4, v8, 6, v9
	v_sub_u32_e32 v4, 0x7f, v4
	s_andn2_saveexec_b64 s[0:1], s[0:1]
	v_lshl_or_b32 v4, v8, 11, s82
	v_add_u32_e32 v4, v4, v9
	s_or_b64 exec, exec, s[0:1]
	v_mul_lo_u32 v6, v6, s84
	v_add_lshl_u32 v224, v6, v7, 1
	v_not_b32_e32 v6, v0
	v_mov_b32_e32 v7, v1
	v_lshlrev_b64 v[14:15], 1, v[0:1]
	v_lshlrev_b64 v[44:45], 1, v[6:7]
	v_lshl_add_u64 v[10:11], s[4:5], 0, v[14:15]
	v_lshl_add_u64 v[12:13], s[66:67], 0, v[44:45]
	v_cmp_gt_i32_e32 vcc, 0, v0
	v_mul_lo_u32 v3, v3, s84
	v_add_lshl_u32 v225, v3, v5, 1
	v_cndmask_b32_e32 v11, v11, v13, vcc
	v_cndmask_b32_e32 v10, v10, v12, vcc
	flat_load_dwordx4 v[32:35], v[10:11]
	v_mov_b32_e32 v3, v1
	v_not_b32_e32 v10, v2
	v_mov_b32_e32 v11, v1
	v_lshlrev_b64 v[62:63], 1, v[2:3]
	v_lshlrev_b64 v[64:65], 1, v[10:11]
	v_lshl_add_u64 v[12:13], s[4:5], 0, v[62:63]
	v_lshl_add_u64 v[36:37], s[66:67], 0, v[64:65]
	v_cmp_gt_i32_e64 s[36:37], 0, v2
	v_mov_b32_e32 v5, v1
	v_mul_lo_u32 v8, v8, s84
	v_cndmask_b32_e64 v13, v13, v37, s[36:37]
	v_cndmask_b32_e64 v12, v12, v36, s[36:37]
	flat_load_dwordx4 v[36:39], v[12:13]
	v_not_b32_e32 v12, v4
	v_mov_b32_e32 v13, v1
	v_lshlrev_b64 v[66:67], 1, v[4:5]
	v_lshlrev_b64 v[68:69], 1, v[12:13]
	v_add_lshl_u32 v199, v8, v9, 1
	v_ashrrev_i32_e32 v8, 3, v56
	v_lshl_add_u64 v[40:41], s[4:5], 0, v[66:67]
	v_lshl_add_u64 v[42:43], s[66:67], 0, v[68:69]
	v_cmp_gt_i32_e64 s[38:39], 0, v4
	v_add_u32_e32 v48, s82, v8
	v_lshlrev_b32_e32 v9, 4, v56
	v_cndmask_b32_e64 v41, v41, v43, s[38:39]
	v_cndmask_b32_e64 v40, v40, v42, s[38:39]
	flat_load_dwordx4 v[40:43], v[40:41]
	v_and_b32_e32 v70, 0x70, v9
	v_mov_b32_e32 v71, v1
	v_ashrrev_i32_e32 v49, 31, v48
	v_lshl_add_u64 v[52:53], s[56:57], 0, v[70:71]
	v_lshlrev_b64 v[72:73], 15, v[48:49]
	v_lshl_add_u64 v[48:49], v[52:53], 0, v[72:73]
	v_lshl_add_u64 v[74:75], v[72:73], 0, s[22:23]
	flat_load_dwordx4 v[48:51], v[48:49]
	v_lshl_add_u64 v[52:53], v[52:53], 0, v[74:75]
	flat_load_dwordx4 v[52:55], v[52:53]
	v_add_u32_e32 v9, 0, v225
	s_movk_i32 s0, 0x88
	v_lshl_add_u64 v[14:15], s[30:31], 0, v[14:15]
	s_waitcnt vmcnt(0) lgkmcnt(0)
	ds_write_b128 v9, v[32:35]
	v_add_u32_e32 v9, 0, v224
	v_lshl_add_u64 v[32:33], s[50:51], 0, v[44:45]
	v_cndmask_b32_e32 v15, v15, v33, vcc
	v_cndmask_b32_e32 v14, v14, v32, vcc
	v_lshl_add_u64 v[32:33], s[50:51], 0, v[64:65]
	ds_write_b128 v9, v[36:39]
	v_add_u32_e32 v9, 0, v199
	ds_write_b128 v9, v[40:43]
	v_mul_lo_u32 v9, v8, s0
	v_add3_u32 v233, 0, v70, v9
	v_add_u32_e32 v9, 0xc800, v233
	v_cmp_lt_i32_e64 s[0:1], 3, v60
	ds_write2_b64 v9, v[48:49], v[50:51] offset1:1
	v_add_u32_e32 v9, 0xea00, v233
	ds_write2_b64 v9, v[52:53], v[54:55] offset1:1
	flat_load_dwordx4 v[176:179], v[14:15]
	v_lshl_add_u64 v[14:15], s[30:31], 0, v[62:63]
	v_cndmask_b32_e64 v15, v15, v33, s[36:37]
	v_cndmask_b32_e64 v14, v14, v32, s[36:37]
	flat_load_dwordx4 v[180:183], v[14:15]
	v_lshl_add_u64 v[14:15], s[30:31], 0, v[66:67]
	v_lshl_add_u64 v[32:33], s[50:51], 0, v[68:69]
	v_cndmask_b32_e64 v15, v15, v33, s[38:39]
	v_cndmask_b32_e64 v14, v14, v32, s[38:39]
	flat_load_dwordx4 v[184:187], v[14:15]
	v_lshl_add_u64 v[14:15], s[44:45], 0, v[70:71]
	v_lshl_add_u64 v[32:33], v[14:15], 0, v[72:73]
	v_lshl_add_u64 v[14:15], v[14:15], 0, v[74:75]
	v_lshl_add_u64 v[32:33], v[32:33], 0, s[74:75]
	v_lshl_add_u64 v[14:15], v[14:15], 0, s[74:75]
	flat_load_dwordx4 v[188:191], v[32:33]
	flat_load_dwordx4 v[192:195], v[14:15]
	s_and_saveexec_b64 s[78:79], s[0:1]
	s_setprio 1
	s_or_b64 exec, exec, s[78:79]
	s_movk_i32 s0, 0x190
	v_mad_u32_u24 v9, v57, s0, 0
	v_mul_i32_i24_e32 v14, 0xfffffef8, v57
	v_lshl_add_u32 v236, v58, 4, v9
	v_add3_u32 v237, v9, v14, v46
	v_ashrrev_i32_e32 v9, 31, v8
	v_lshlrev_b64 v[14:15], 15, v[8:9]
	v_and_b32_e32 v9, 7, v56
	v_add_u32_e32 v8, s69, v8
	v_lshlrev_b32_e32 v32, 4, v9
	v_ashrrev_i32_e32 v9, 31, v8
	v_lshl_add_u64 v[14:15], s[62:63], 0, v[14:15]
	v_mov_b32_e32 v33, v1
	v_lshlrev_b64 v[8:9], 15, v[8:9]
	v_lshl_add_u64 v[200:201], v[14:15], 0, v[32:33]
	v_lshl_add_u64 v[8:9], s[60:61], 0, v[8:9]
	v_mov_b32_e32 v14, v1
	v_mov_b32_e32 v15, v1
	s_lshl_b32 s92, s6, 2
	v_or_b32_e32 v235, 31, v59
	v_lshlrev_b32_e32 v234, 2, v58
	v_lshl_add_u64 v[202:203], v[8:9], 0, v[32:33]
	v_lshl_add_u64 v[204:205], v[4:5], 1, s[70:71]
	v_lshl_add_u64 v[214:215], v[2:3], 1, s[70:71]
	v_lshl_add_u64 v[216:217], v[0:1], 1, s[70:71]
	v_lshl_add_u64 v[218:219], v[12:13], 1, s[72:73]
	v_lshl_add_u64 v[220:221], v[10:11], 1, s[72:73]
	v_lshl_add_u64 v[222:223], v[6:7], 1, s[72:73]
	v_mov_b32_e32 v0, v1
	v_mov_b32_e32 v2, v1
	v_mov_b32_e32 v3, v1
	v_mov_b32_e32 v4, v1
	v_mov_b32_e32 v5, v1
	v_mov_b32_e32 v6, v1
	v_mov_b32_e32 v7, v1
	v_mov_b32_e32 v8, v1
	v_mov_b32_e32 v9, v1
	v_mov_b32_e32 v10, v1
	v_mov_b32_e32 v11, v1
	v_mov_b32_e32 v12, v1
	v_mov_b32_e32 v13, v1
	v_mov_b64_e32 v[46:47], v[14:15]
	v_mov_b64_e32 v[62:63], v[14:15]
	v_mov_b64_e32 v[78:79], v[14:15]
	v_mov_b64_e32 v[94:95], v[14:15]
	s_xor_b64 s[78:79], s[76:77], -1
	s_mov_b32 s7, 2
	s_add_i32 s6, s92, 4
	s_addk_i32 s68, 0x100
	s_mov_b32 s85, 0
	v_mov_b32_e32 v238, 0
	v_mov_b64_e32 v[44:45], v[12:13]
	v_mov_b64_e32 v[42:43], v[10:11]
	v_mov_b64_e32 v[40:41], v[8:9]
	v_mov_b64_e32 v[38:39], v[6:7]
	v_mov_b64_e32 v[36:37], v[4:5]
	v_mov_b64_e32 v[34:35], v[2:3]
	v_mov_b64_e32 v[32:33], v[0:1]
	v_mov_b64_e32 v[60:61], v[12:13]
	v_mov_b64_e32 v[58:59], v[10:11]
	v_mov_b64_e32 v[56:57], v[8:9]
	v_mov_b64_e32 v[54:55], v[6:7]
	v_mov_b64_e32 v[52:53], v[4:5]
	v_mov_b64_e32 v[50:51], v[2:3]
	v_mov_b64_e32 v[48:49], v[0:1]
	v_mov_b64_e32 v[76:77], v[12:13]
	v_mov_b64_e32 v[74:75], v[10:11]
	v_mov_b64_e32 v[72:73], v[8:9]
	v_mov_b64_e32 v[70:71], v[6:7]
	v_mov_b64_e32 v[68:69], v[4:5]
	v_mov_b64_e32 v[66:67], v[2:3]
	v_mov_b64_e32 v[64:65], v[0:1]
	v_mov_b64_e32 v[92:93], v[12:13]
	v_mov_b64_e32 v[90:91], v[10:11]
	v_mov_b64_e32 v[88:89], v[8:9]
	v_mov_b64_e32 v[86:87], v[6:7]
	v_mov_b64_e32 v[84:85], v[4:5]
	v_mov_b64_e32 v[82:83], v[2:3]
	v_mov_b64_e32 v[80:81], v[0:1]
	v_lshl_add_u64 v[2:3], s[8:9], 0, v[216:217]
	v_lshl_add_u64 v[4:5], s[8:9], 0, v[222:223]
	v_cndmask_b32_e32 v217, v3, v5, vcc
	v_cndmask_b32_e32 v216, v2, v4, vcc
	v_lshl_add_u64 v[2:3], s[8:9], 0, v[214:215]
	v_lshl_add_u64 v[4:5], s[8:9], 0, v[220:221]
	v_cndmask_b32_e64 v215, v3, v5, s[36:37]
	v_cndmask_b32_e64 v214, v2, v4, s[36:37]
	v_lshl_add_u64 v[2:3], s[8:9], 0, v[204:205]
	v_lshl_add_u64 v[4:5], s[8:9], 0, v[218:219]
	v_cndmask_b32_e64 v205, v3, v5, s[38:39]
	v_cndmask_b32_e64 v204, v2, v4, s[38:39]
	v_mov_b32_e32 v2, s24
	v_mov_b32_e32 v3, s25
	v_mov_b32_e32 v4, s26
	v_mov_b32_e32 v5, s27
	v_cndmask_b32_e32 v222, v2, v4, vcc
	v_cndmask_b32_e32 v223, v3, v5, vcc
	v_cndmask_b32_e64 v220, v2, v4, s[36:37]
	v_cndmask_b32_e64 v221, v3, v5, s[36:37]
	v_cndmask_b32_e64 v218, v2, v4, s[38:39]
	v_cndmask_b32_e64 v219, v3, v5, s[38:39]
	v_lshl_add_u64 v[200:201], s[8:9], 0, v[200:201]
	v_lshl_add_u64 v[202:203], s[8:9], 0, v[202:203]
	s_branch .LBB0_398

.LBB0_738:
	s_ashr_i32 s0, s12, 9
	s_ashr_i32 s1, s0, 31
	s_lshl_b64 s[14:15], s[0:1], 13
	s_lshl_b32 s0, s12, 7
	s_ashr_i32 s13, s12, 31
	s_and_b32 s0, s0, 0x1f80
	s_lshl_b64 s[18:19], s[12:13], 18
	s_bfe_u32 s2, s12, 0x30006
	s_or_b32 s14, s14, s0
	s_add_u32 s0, s4, s18
	s_addc_u32 s1, s5, s19
	s_lshl_b32 s13, s2, 9
	v_readlane_b32 s6, v254, 30
	s_waitcnt vmcnt(0)
	v_ashrrev_i32_e32 v4, 5, v251
	v_readlane_b32 s7, v254, 31
	s_add_u32 s6, s6, s13
	v_lshlrev_b32_e32 v0, 4, v251
	v_ashrrev_i32_e32 v5, 31, v4
	s_addc_u32 s7, s7, 0
	v_and_b32_e32 v2, 0x1f0, v0
	v_mov_b32_e32 v3, v1
	v_lshl_add_u64 v[6:7], s[14:15], 0, v[4:5]
	v_lshl_add_u64 v[38:39], s[6:7], 0, v[2:3]
	v_lshlrev_b64 v[6:7], 12, v[6:7]
	v_lshl_add_u64 v[6:7], v[38:39], 0, v[6:7]
	flat_load_dwordx4 v[34:37], v[6:7]
	v_add_u32_e32 v3, 0x200, v251
	v_and_b32_e32 v6, 0xffffffcf, v251
	v_ashrrev_i32_e32 v40, 5, v3
	v_ashrrev_i32_e32 v7, 31, v6
	v_ashrrev_i32_e32 v41, 31, v40
	v_bfe_u32 v252, v251, 4, 2
	v_lshlrev_b64 v[66:67], 9, v[6:7]
	v_add_u32_e32 v42, 0, v2
	v_lshl_add_u64 v[2:3], s[14:15], 0, v[40:41]
	v_lshlrev_b32_e32 v0, 4, v252
	v_lshlrev_b64 v[46:47], 12, v[2:3]
	v_lshl_add_u64 v[2:3], s[0:1], 0, v[66:67]
	s_movk_i32 s10, 0x210
	v_lshl_add_u64 v[2:3], v[2:3], 0, v[0:1]
	s_movk_i32 s0, 0x2000
	v_mad_u64_u32 v[44:45], s[6:7], v4, s10, v[42:43]
	v_add_co_u32_e32 v4, vcc, s0, v2
	s_movk_i32 s0, 0x4000
	s_nop 0
	v_addc_co_u32_e32 v5, vcc, 0, v3, vcc
	v_add_co_u32_e32 v6, vcc, s0, v2
	v_lshl_add_u64 v[46:47], v[38:39], 0, v[46:47]
	s_nop 0
	v_addc_co_u32_e32 v7, vcc, 0, v3, vcc
	v_add_co_u32_e32 v48, vcc, s75, v2
	v_add_u32_e32 v41, 0x400, v251
	s_nop 0
	v_addc_co_u32_e32 v49, vcc, 0, v3, vcc
	flat_load_dwordx4 v[18:21], v[2:3]
	flat_load_dwordx4 v[14:17], v[2:3] offset:64
	flat_load_dwordx4 v[22:25], v[4:5]
	flat_load_dwordx4 v[10:13], v[4:5] offset:64
	flat_load_dwordx4 v[26:29], v[6:7]
	s_nop 0
	flat_load_dwordx4 v[6:9], v[6:7] offset:64
	s_nop 0
	flat_load_dwordx4 v[30:33], v[48:49]
	flat_load_dwordx4 v[2:5], v[48:49] offset:64
	v_ashrrev_i32_e32 v226, 6, v251
	v_and_b32_e32 v217, 15, v251
	s_movk_i32 s30, 0x210
	s_waitcnt vmcnt(0) lgkmcnt(0)
	ds_write_b128 v44, v[34:37]
	flat_load_dwordx4 v[34:37], v[46:47]
	v_ashrrev_i32_e32 v44, 5, v41
	v_ashrrev_i32_e32 v45, 31, v44
	v_lshl_add_u64 v[46:47], s[14:15], 0, v[44:45]
	v_mad_u64_u32 v[40:41], s[0:1], v40, s10, v[42:43]
	v_lshlrev_b64 v[46:47], 12, v[46:47]
	v_lshl_add_u64 v[46:47], v[38:39], 0, v[46:47]
	v_mad_u64_u32 v[44:45], s[0:1], v44, s10, v[42:43]
	s_waitcnt vmcnt(0) lgkmcnt(0)
	ds_write_b128 v40, v[34:37]
	flat_load_dwordx4 v[34:37], v[46:47]
	v_add_u32_e32 v40, 0x600, v251
	v_ashrrev_i32_e32 v40, 5, v40
	v_ashrrev_i32_e32 v41, 31, v40
	v_lshl_add_u64 v[46:47], s[14:15], 0, v[40:41]
	v_lshlrev_b64 v[46:47], 12, v[46:47]
	v_lshl_add_u64 v[46:47], v[38:39], 0, v[46:47]
	v_add_u32_e32 v41, 0x800, v251
	s_waitcnt vmcnt(0) lgkmcnt(0)
	ds_write_b128 v44, v[34:37]
	flat_load_dwordx4 v[34:37], v[46:47]
	v_ashrrev_i32_e32 v44, 5, v41
	v_ashrrev_i32_e32 v45, 31, v44
	v_lshl_add_u64 v[46:47], s[14:15], 0, v[44:45]
	v_mad_u64_u32 v[40:41], s[0:1], v40, s10, v[42:43]
	v_lshlrev_b64 v[46:47], 12, v[46:47]
	v_lshl_add_u64 v[46:47], v[38:39], 0, v[46:47]
	v_mad_u64_u32 v[44:45], s[0:1], v44, s10, v[42:43]
	s_waitcnt vmcnt(0) lgkmcnt(0)
	ds_write_b128 v40, v[34:37]
	flat_load_dwordx4 v[34:37], v[46:47]
	v_add_u32_e32 v40, 0xa00, v251
	v_ashrrev_i32_e32 v40, 5, v40
	v_ashrrev_i32_e32 v41, 31, v40
	v_lshl_add_u64 v[46:47], s[14:15], 0, v[40:41]
	v_lshlrev_b64 v[46:47], 12, v[46:47]
	v_lshl_add_u64 v[46:47], v[38:39], 0, v[46:47]
	v_add_u32_e32 v41, 0xc00, v251
	s_waitcnt vmcnt(0) lgkmcnt(0)
	ds_write_b128 v44, v[34:37]
	flat_load_dwordx4 v[34:37], v[46:47]
	v_ashrrev_i32_e32 v44, 5, v41
	v_ashrrev_i32_e32 v45, 31, v44
	v_lshl_add_u64 v[46:47], s[14:15], 0, v[44:45]
	v_mad_u64_u32 v[40:41], s[0:1], v40, s10, v[42:43]
	v_lshlrev_b64 v[46:47], 12, v[46:47]
	v_lshl_add_u64 v[46:47], v[38:39], 0, v[46:47]
	s_waitcnt vmcnt(0) lgkmcnt(0)
	ds_write_b128 v40, v[34:37]
	flat_load_dwordx4 v[34:37], v[46:47]
	v_add_u32_e32 v40, 0xe00, v251
	v_ashrrev_i32_e32 v46, 5, v40
	v_ashrrev_i32_e32 v47, 31, v46
	v_mad_u64_u32 v[40:41], s[0:1], v44, s10, v[42:43]
	v_lshl_add_u64 v[44:45], s[14:15], 0, v[46:47]
	v_lshlrev_b64 v[44:45], 12, v[44:45]
	v_lshl_add_u64 v[38:39], v[38:39], 0, v[44:45]
	v_mad_u64_u32 v[42:43], s[6:7], v46, s10, v[42:43]
	s_waitcnt vmcnt(0) lgkmcnt(0)
	ds_write_b128 v40, v[34:37]
	flat_load_dwordx4 v[38:41], v[38:39]
	v_ashrrev_i32_e32 v36, 7, v251
	v_and_b32_e32 v34, 1, v226
	v_lshlrev_b32_e32 v35, 3, v252
	v_cmp_lt_i32_e32 vcc, 1, v36
	v_cmp_eq_u32_e64 s[0:1], 0, v34
	v_lshlrev_b32_e32 v214, 1, v35
	s_or_b64 s[0:1], vcc, s[0:1]
	v_lshl_or_b32 v68, v36, 5, v217
	s_waitcnt vmcnt(0) lgkmcnt(0)
	ds_write_b128 v42, v[38:41]
	s_waitcnt lgkmcnt(0)
	s_barrier
	s_and_saveexec_b64 s[6:7], s[0:1]
	s_xor_b64 s[0:1], exec, s[6:7]
	s_cbranch_execz .LBB0_740
	v_lshlrev_b32_e32 v69, 6, v34
	v_or3_b32 v34, v69, v217, s14
	v_mov_b32_e32 v35, s15
	s_lshl_b32 s2, s2, 8
	v_lshlrev_b64 v[34:35], 12, v[34:35]
	v_lshl_add_u64 v[34:35], s[44:45], 0, v[34:35]
	s_lshl_b32 s54, s2, 1
	v_lshl_add_u64 v[34:35], v[34:35], 0, s[54:55]
	v_mov_b32_e32 v215, v1
	v_lshl_add_u64 v[34:35], v[34:35], 0, v[214:215]
	v_add_co_u32_e32 v166, vcc, s56, v34
	s_nop 1
	v_addc_co_u32_e32 v167, vcc, 0, v35, vcc
	v_add_co_u32_e32 v168, vcc, s57, v34
	s_nop 1
	v_addc_co_u32_e32 v169, vcc, 0, v35, vcc
	v_add_co_u32_e32 v170, vcc, s83, v34
	s_nop 1
	v_addc_co_u32_e32 v171, vcc, 0, v35, vcc
	global_load_dwordx4 v[102:105], v[34:35], off
	global_load_dwordx4 v[106:109], v[34:35], off offset:64
	global_load_dwordx4 v[110:113], v[34:35], off offset:128
	global_load_dwordx4 v[114:117], v[166:167], off
	global_load_dwordx4 v[118:121], v[168:169], off
	global_load_dwordx4 v[122:125], v[170:171], off
	global_load_dwordx4 v[126:129], v[166:167], off offset:64
	global_load_dwordx4 v[130:133], v[168:169], off offset:64
	global_load_dwordx4 v[134:137], v[170:171], off offset:64
	global_load_dwordx4 v[138:141], v[166:167], off offset:128
	global_load_dwordx4 v[142:145], v[34:35], off offset:192
	global_load_dwordx4 v[146:149], v[168:169], off offset:128
	global_load_dwordx4 v[150:153], v[170:171], off offset:128
	global_load_dwordx4 v[154:157], v[166:167], off offset:192
	global_load_dwordx4 v[158:161], v[168:169], off offset:192
	global_load_dwordx4 v[162:165], v[170:171], off offset:192
	global_load_dwordx4 v[174:177], v[34:35], off offset:256
	global_load_dwordx4 v[178:181], v[166:167], off offset:256
	global_load_dwordx4 v[182:185], v[168:169], off offset:256
	global_load_dwordx4 v[186:189], v[170:171], off offset:256
	global_load_dwordx4 v[190:193], v[34:35], off offset:320
	global_load_dwordx4 v[194:197], v[166:167], off offset:320
	global_load_dwordx4 v[198:201], v[168:169], off offset:320
	global_load_dwordx4 v[202:205], v[170:171], off offset:320
	global_load_dwordx4 v[208:211], v[34:35], off offset:384
	global_load_dwordx4 v[230:233], v[166:167], off offset:384
	global_load_dwordx4 v[234:237], v[168:169], off offset:384
	global_load_dwordx4 v[238:241], v[170:171], off offset:384
	global_load_dwordx4 v[242:245], v[34:35], off offset:448
	global_load_dwordx4 v[246:249], v[166:167], off offset:448
	v_lshl_or_b32 v68, v36, 5, v217
	v_mul_lo_u32 v36, v68, s30
	v_add3_u32 v40, 0, v214, v36
	ds_read_b128 v[46:49], v40
	ds_read_b128 v[50:53], v40 offset:8448
	v_add_co_u32_e32 v36, vcc, s56, v34
	v_addc_co_u32_e32 v37, vcc, 0, v35, vcc
	v_add_co_u32_e32 v38, vcc, s57, v34
	ds_read_b128 v[82:85], v40 offset:64
	ds_read_b128 v[90:93], v40 offset:8512
	v_addc_co_u32_e32 v39, vcc, 0, v35, vcc
	s_mov_b32 s54, 0x34000
	s_waitcnt vmcnt(0) lgkmcnt(0)
	v_mov_b32_e32 v42, v102
	v_mov_b32_e32 v43, v103
	v_mov_b32_e32 v44, v104
	v_mov_b32_e32 v45, v105
	v_mov_b32_e32 v78, v106
	v_mov_b32_e32 v79, v107
	v_mov_b32_e32 v80, v108
	v_mov_b32_e32 v81, v109
	v_mov_b32_e32 v94, v110
	v_mov_b32_e32 v95, v111
	v_mov_b32_e32 v96, v112
	v_mov_b32_e32 v97, v113
	s_nop 1
	v_mfma_f32_16x16x32_bf16 v[54:57], v[42:45], v[46:49], 0
	ds_read_b128 v[98:101], v40 offset:8576
	v_mfma_f32_16x16x32_bf16 v[58:61], v[42:45], v[50:53], 0
	s_waitcnt lgkmcnt(0)
	v_mov_b32_e32 v42, v114
	v_mov_b32_e32 v43, v115
	v_mov_b32_e32 v44, v116
	v_mov_b32_e32 v45, v117
	s_nop 1
	v_mfma_f32_16x16x32_bf16 v[62:65], v[42:45], v[46:49], 0
	v_mfma_f32_16x16x32_bf16 v[70:73], v[42:45], v[50:53], 0
	s_waitcnt lgkmcnt(0)
	v_mov_b32_e32 v42, v118
	v_mov_b32_e32 v43, v119
	v_mov_b32_e32 v44, v120
	v_mov_b32_e32 v45, v121
	s_nop 1
	v_mfma_f32_16x16x32_bf16 v[74:77], v[42:45], v[46:49], 0
	v_mfma_f32_16x16x32_bf16 v[86:89], v[42:45], v[50:53], 0
	v_add_co_u32_e32 v42, vcc, s83, v34
	s_nop 1
	v_addc_co_u32_e32 v43, vcc, 0, v35, vcc
	v_mfma_f32_16x16x32_bf16 v[54:57], v[78:81], v[82:85], v[54:57]
	v_mfma_f32_16x16x32_bf16 v[58:61], v[78:81], v[90:93], v[58:61]
	s_waitcnt lgkmcnt(0)
	v_mov_b32_e32 v78, v122
	v_mov_b32_e32 v79, v123
	v_mov_b32_e32 v80, v124
	v_mov_b32_e32 v81, v125
	s_nop 1
	v_mfma_f32_16x16x32_bf16 v[44:47], v[78:81], v[46:49], 0
	v_mfma_f32_16x16x32_bf16 v[48:51], v[78:81], v[50:53], 0
	s_waitcnt lgkmcnt(0)
	v_mov_b32_e32 v78, v126
	v_mov_b32_e32 v79, v127
	v_mov_b32_e32 v80, v128
	v_mov_b32_e32 v81, v129
	s_nop 1
	v_mfma_f32_16x16x32_bf16 v[62:65], v[78:81], v[82:85], v[62:65]
	v_mfma_f32_16x16x32_bf16 v[70:73], v[78:81], v[90:93], v[70:73]
	s_waitcnt lgkmcnt(0)
	v_mov_b32_e32 v78, v130
	v_mov_b32_e32 v79, v131
	v_mov_b32_e32 v80, v132
	v_mov_b32_e32 v81, v133
	s_nop 1
	v_mfma_f32_16x16x32_bf16 v[74:77], v[78:81], v[82:85], v[74:77]
	v_mfma_f32_16x16x32_bf16 v[78:81], v[78:81], v[90:93], v[86:89]
	s_nop 2
	ds_read_b128 v[86:89], v40 offset:128
	s_waitcnt lgkmcnt(0)
	v_mfma_f32_16x16x32_bf16 v[52:55], v[94:97], v[86:89], v[54:57]
	v_mfma_f32_16x16x32_bf16 v[56:59], v[94:97], v[98:101], v[58:61]
	s_waitcnt lgkmcnt(0)
	v_mov_b32_e32 v94, v134
	v_mov_b32_e32 v95, v135
	v_mov_b32_e32 v96, v136
	v_mov_b32_e32 v97, v137
	s_nop 1
	v_mfma_f32_16x16x32_bf16 v[44:47], v[94:97], v[82:85], v[44:47]
	v_mfma_f32_16x16x32_bf16 v[48:51], v[94:97], v[90:93], v[48:51]
	ds_read_b128 v[94:97], v40 offset:8640
	s_waitcnt lgkmcnt(0)
	v_mov_b32_e32 v82, v138
	v_mov_b32_e32 v83, v139
	v_mov_b32_e32 v84, v140
	v_mov_b32_e32 v85, v141
	v_mov_b32_e32 v90, v142
	v_mov_b32_e32 v91, v143
	v_mov_b32_e32 v92, v144
	v_mov_b32_e32 v93, v145
	s_nop 1
	v_mfma_f32_16x16x32_bf16 v[60:63], v[82:85], v[86:89], v[62:65]
	v_mfma_f32_16x16x32_bf16 v[70:73], v[82:85], v[98:101], v[70:73]
	s_waitcnt lgkmcnt(0)
	v_mov_b32_e32 v82, v146
	v_mov_b32_e32 v83, v147
	v_mov_b32_e32 v84, v148
	v_mov_b32_e32 v85, v149
	s_nop 1
	v_mfma_f32_16x16x32_bf16 v[74:77], v[82:85], v[86:89], v[74:77]
	v_mfma_f32_16x16x32_bf16 v[78:81], v[82:85], v[98:101], v[78:81]
	ds_read_b128 v[82:85], v40 offset:192
	s_waitcnt lgkmcnt(0)
	v_mfma_f32_16x16x32_bf16 v[52:55], v[90:93], v[82:85], v[52:55]
	v_mfma_f32_16x16x32_bf16 v[56:59], v[90:93], v[94:97], v[56:59]
	s_waitcnt lgkmcnt(0)
	v_mov_b32_e32 v90, v150
	v_mov_b32_e32 v91, v151
	v_mov_b32_e32 v92, v152
	v_mov_b32_e32 v93, v153
	s_nop 1
	v_mfma_f32_16x16x32_bf16 v[44:47], v[90:93], v[86:89], v[44:47]
	v_mfma_f32_16x16x32_bf16 v[48:51], v[90:93], v[98:101], v[48:51]
	ds_read_b128 v[90:93], v40 offset:8704
	ds_read_b128 v[98:101], v40 offset:8896
	s_waitcnt lgkmcnt(0)
	v_mov_b32_e32 v86, v154
	v_mov_b32_e32 v87, v155
	v_mov_b32_e32 v88, v156
	v_mov_b32_e32 v89, v157
	s_nop 1
	v_mfma_f32_16x16x32_bf16 v[60:63], v[86:89], v[82:85], v[60:63]
	v_mfma_f32_16x16x32_bf16 v[70:73], v[86:89], v[94:97], v[70:73]
	s_waitcnt lgkmcnt(0)
	v_mov_b32_e32 v86, v158
	v_mov_b32_e32 v87, v159
	v_mov_b32_e32 v88, v160
	v_mov_b32_e32 v89, v161
	s_nop 1
	v_mfma_f32_16x16x32_bf16 v[74:77], v[86:89], v[82:85], v[74:77]
	v_mfma_f32_16x16x32_bf16 v[78:81], v[86:89], v[94:97], v[78:81]
	s_waitcnt lgkmcnt(0)
	v_mov_b32_e32 v86, v162
	v_mov_b32_e32 v87, v163
	v_mov_b32_e32 v88, v164
	v_mov_b32_e32 v89, v165
	s_nop 1
	v_mfma_f32_16x16x32_bf16 v[44:47], v[86:89], v[82:85], v[44:47]
	v_mfma_f32_16x16x32_bf16 v[48:51], v[86:89], v[94:97], v[48:51]
	ds_read_b128 v[86:89], v40 offset:256
	s_waitcnt lgkmcnt(0)
	v_mov_b32_e32 v82, v174
	v_mov_b32_e32 v83, v175
	v_mov_b32_e32 v84, v176
	v_mov_b32_e32 v85, v177
	s_nop 1
	v_mfma_f32_16x16x32_bf16 v[52:55], v[82:85], v[86:89], v[52:55]
	v_mfma_f32_16x16x32_bf16 v[56:59], v[82:85], v[90:93], v[56:59]
	s_waitcnt lgkmcnt(0)
	v_mov_b32_e32 v82, v178
	v_mov_b32_e32 v83, v179
	v_mov_b32_e32 v84, v180
	v_mov_b32_e32 v85, v181
	s_nop 1
	v_mfma_f32_16x16x32_bf16 v[60:63], v[82:85], v[86:89], v[60:63]
	v_mfma_f32_16x16x32_bf16 v[70:73], v[82:85], v[90:93], v[70:73]
	s_waitcnt lgkmcnt(0)
	v_mov_b32_e32 v82, v182
	v_mov_b32_e32 v83, v183
	v_mov_b32_e32 v84, v184
	v_mov_b32_e32 v85, v185
	s_nop 1
	v_mfma_f32_16x16x32_bf16 v[74:77], v[82:85], v[86:89], v[74:77]
	v_mfma_f32_16x16x32_bf16 v[78:81], v[82:85], v[90:93], v[78:81]
	s_waitcnt lgkmcnt(0)
	v_mov_b32_e32 v82, v186
	v_mov_b32_e32 v83, v187
	v_mov_b32_e32 v84, v188
	v_mov_b32_e32 v85, v189
	s_nop 1
	v_mfma_f32_16x16x32_bf16 v[44:47], v[82:85], v[86:89], v[44:47]
	v_mfma_f32_16x16x32_bf16 v[48:51], v[82:85], v[90:93], v[48:51]
	ds_read_b128 v[82:85], v40 offset:320
	ds_read_b128 v[90:93], v40 offset:8768
	s_waitcnt lgkmcnt(0)
	v_mov_b32_e32 v86, v190
	v_mov_b32_e32 v87, v191
	v_mov_b32_e32 v88, v192
	v_mov_b32_e32 v89, v193
	s_nop 1
	v_mfma_f32_16x16x32_bf16 v[52:55], v[86:89], v[82:85], v[52:55]
	v_mfma_f32_16x16x32_bf16 v[56:59], v[86:89], v[90:93], v[56:59]
	s_waitcnt lgkmcnt(0)
	v_mov_b32_e32 v86, v194
	v_mov_b32_e32 v87, v195
	v_mov_b32_e32 v88, v196
	v_mov_b32_e32 v89, v197
	s_nop 1
	v_mfma_f32_16x16x32_bf16 v[60:63], v[86:89], v[82:85], v[60:63]
	v_mfma_f32_16x16x32_bf16 v[70:73], v[86:89], v[90:93], v[70:73]
	s_waitcnt lgkmcnt(0)
	v_mov_b32_e32 v86, v198
	v_mov_b32_e32 v87, v199
	v_mov_b32_e32 v88, v200
	v_mov_b32_e32 v89, v201
	s_nop 1
	v_mfma_f32_16x16x32_bf16 v[74:77], v[86:89], v[82:85], v[74:77]
	v_mfma_f32_16x16x32_bf16 v[78:81], v[86:89], v[90:93], v[78:81]
	s_waitcnt lgkmcnt(0)
	v_mov_b32_e32 v86, v202
	v_mov_b32_e32 v87, v203
	v_mov_b32_e32 v88, v204
	v_mov_b32_e32 v89, v205
	s_nop 1
	v_mfma_f32_16x16x32_bf16 v[44:47], v[86:89], v[82:85], v[44:47]
	v_mfma_f32_16x16x32_bf16 v[48:51], v[86:89], v[90:93], v[48:51]
	ds_read_b128 v[86:89], v40 offset:384
	ds_read_b128 v[90:93], v40 offset:8832
	s_waitcnt lgkmcnt(0)
	v_mov_b32_e32 v82, v208
	v_mov_b32_e32 v83, v209
	v_mov_b32_e32 v84, v210
	v_mov_b32_e32 v85, v211
	s_nop 1
	v_mfma_f32_16x16x32_bf16 v[52:55], v[82:85], v[86:89], v[52:55]
	v_mfma_f32_16x16x32_bf16 v[56:59], v[82:85], v[90:93], v[56:59]
	s_waitcnt lgkmcnt(0)
	v_mov_b32_e32 v82, v230
	v_mov_b32_e32 v83, v231
	v_mov_b32_e32 v84, v232
	v_mov_b32_e32 v85, v233
	s_nop 1
	v_mfma_f32_16x16x32_bf16 v[94:97], v[82:85], v[86:89], v[60:63]
	s_nop 2
	s_waitcnt lgkmcnt(0)
	v_mov_b32_e32 v60, v234
	v_mov_b32_e32 v61, v235
	v_mov_b32_e32 v62, v236
	v_mov_b32_e32 v63, v237
	s_nop 1
	v_mfma_f32_16x16x32_bf16 v[74:77], v[60:63], v[86:89], v[74:77]
	v_mfma_f32_16x16x32_bf16 v[78:81], v[60:63], v[90:93], v[78:81]
	v_mfma_f32_16x16x32_bf16 v[70:73], v[82:85], v[90:93], v[70:73]
	s_waitcnt lgkmcnt(0)
	v_mov_b32_e32 v60, v238
	v_mov_b32_e32 v61, v239
	v_mov_b32_e32 v62, v240
	v_mov_b32_e32 v63, v241
	s_nop 1
	v_mfma_f32_16x16x32_bf16 v[82:85], v[60:63], v[86:89], v[44:47]
	s_nop 2
	s_nop 0
	v_mfma_f32_16x16x32_bf16 v[86:89], v[60:63], v[90:93], v[48:51]
	ds_read_b128 v[90:93], v40 offset:448
	s_waitcnt lgkmcnt(0)
	v_mov_b32_e32 v44, v242
	v_mov_b32_e32 v45, v243
	v_mov_b32_e32 v46, v244
	v_mov_b32_e32 v47, v245
	v_mov_b32_e32 v34, v246
	v_mov_b32_e32 v35, v247
	v_mov_b32_e32 v36, v248
	v_mov_b32_e32 v37, v249
	s_nop 1
	v_mfma_f32_16x16x32_bf16 v[62:65], v[44:47], v[90:93], v[52:55]
	v_mfma_f32_16x16x32_bf16 v[58:61], v[44:47], v[98:101], v[56:59]
	v_mfma_f32_16x16x32_bf16 v[54:57], v[34:37], v[90:93], v[94:97]
	v_mfma_f32_16x16x32_bf16 v[50:53], v[34:37], v[98:101], v[70:73]
	global_load_dwordx4 v[102:105], v[168:169], off offset:448
	global_load_dwordx4 v[106:109], v[170:171], off offset:448
	s_waitcnt vmcnt(0) lgkmcnt(0)
	v_mov_b32_e32 v34, v102
	v_mov_b32_e32 v35, v103
	v_mov_b32_e32 v36, v104
	v_mov_b32_e32 v37, v105
	s_nop 1
	v_mfma_f32_16x16x32_bf16 v[46:49], v[34:37], v[90:93], v[74:77]
	v_or_b32_e32 v70, 16, v68
	v_mfma_f32_16x16x32_bf16 v[38:41], v[34:37], v[98:101], v[78:81]
	s_waitcnt lgkmcnt(0)
	v_mov_b32_e32 v34, v106
	v_mov_b32_e32 v35, v107
	v_mov_b32_e32 v36, v108
	v_mov_b32_e32 v37, v109
	s_nop 1
	v_mfma_f32_16x16x32_bf16 v[42:45], v[34:37], v[90:93], v[82:85]
	v_mfma_f32_16x16x32_bf16 v[34:37], v[34:37], v[98:101], v[86:89]
